# GEMM modes 0/2: five of the sixteen output stores per thread deferred into the first K iterations of the next tile (held in spare registers)
# speedup vs baseline: 1.0012x; 1.0012x over previous
; #define G5_LOAD(k0)                                                                 \
;   {                                                                                 \
;     _Pragma("unroll") for (int i_ = 0; i_ < 4; ++i_) ra[i_] = ldg16(Ap + (size_t)(i_ * 64) * lda + (k0)); \
;     _Pragma("unroll") for (int i_ = 0; i_ < 4; ++i_) rb[i_] = ldg16(Bp + (size_t)(i_ * 64) * ldb + (k0)); \
;   }
; #define G5_STORE(s)                                                                 \
;   {                                                                                 \
;     _Pragma("unroll") for (int i_ = 0; i_ < 4; ++i_) *(u32x4*)(Sw + (s) * STG + i_ * 64 * GS) = ra[i_]; \
;     _Pragma("unroll") for (int i_ = 0; i_ < 4; ++i_) *(u32x4*)(Sw + (s) * STG + 256 * GS + i_ * 64 * GS) = rb[i_]; \
;   }
; template <typename Epi>
; DI void gemm_tile512(const u16* __restrict__ A, int lda, const u16* __restrict__ Bt, int ldb, int K, char* lds_all, Epi epi) {
;     ...
;   const int nk = K >> 6;
;   __syncthreads();
;   G5_LOAD(0);
;   G5_STORE(0);
;   G5_LOAD(64);
;   __syncthreads();
;   for (int kt = 0; kt + 2 < nk; ++kt) {
;     const int cur = kt & 1;
;     G5_COMPUTE(cur);
;     G5_STORE(cur ^ 1);
;     G5_LOAD((kt + 2) << 6);
;     __syncthreads();
;   }
; DI void gemm_phase(const Params& p, int layer, int mode, int nrows, char* lds_all) {
;     ...
;   for (int i = jb;; i += nj) {
;     const int srl = i / per, rem = i - srl * per;
;     const int sr = xcd + nx * srl;
;     if (sr >= nsr) break;
;     const int tn = rem >> 1, tm = sr * 2 + (rem & 1);
;     const int m0 = tm * 256, n0 = tn * 256;
;     gemm_tile512(A + (size_t)m0 * lda, lda, Bt + (size_t)n0 * ldb, ldb, K, lds_all, [&](int half) {
.LBB0_198:
	s_mov_b32 s32, 0
	s_mul_i32 s6, s4, 0xffffffea
	s_lshl_b32 s11, s5, 9
	s_lshl_b32 s5, s16, 8
	s_add_i32 s6, s6, s16
	s_and_b32 s5, s5, 0x100
	s_or_b32 s17, s5, s11
	s_lshl_b32 s5, s6, 7
	s_and_b32 s18, s5, 0xffffff00
	s_mul_i32 s6, s17, 0x900
	v_readlane_b32 s7, v250, 46
	s_mul_hi_i32 s5, s17, 0x900
	s_add_u32 s6, s7, s6
	v_readlane_b32 s7, v250, 47
	s_addc_u32 s7, s7, s5
	s_mul_i32 s8, s18, 0x900
	s_mul_hi_i32 s5, s18, 0x900
	s_add_u32 s8, s2, s8
	s_addc_u32 s9, s3, s5
	s_mov_b64 s[98:99], s[6:7]
	s_mov_b64 s[100:101], s[8:9]
	v_lshrrev_b32_e32 v239, 3, v165
	v_and_b32_e32 v0, 7, v165
	v_mul_u32_u24_e32 v206, 0x900, v239
	v_lshl_add_u32 v206, v0, 4, v206
	v_add_u32_e32 v207, 0x24000, v206
	v_add_u32_e32 v208, 0x48000, v206
	v_add_u32_e32 v238, 0x6c000, v206
	global_load_dwordx4 v[130:133], v206, s[98:99]
	global_load_dwordx4 v[134:137], v207, s[98:99]
	global_load_dwordx4 v[138:141], v208, s[98:99]
	global_load_dwordx4 v[142:145], v238, s[98:99]
	global_load_dwordx4 v[146:149], v206, s[100:101]
	global_load_dwordx4 v[150:153], v207, s[100:101]
	global_load_dwordx4 v[154:157], v208, s[100:101]
	global_load_dwordx4 v[158:161], v238, s[100:101]
	global_load_dwordx4 v[218:221], v206, s[98:99] offset:128
	global_load_dwordx4 v[222:225], v207, s[98:99] offset:128
	global_load_dwordx4 v[226:229], v208, s[98:99] offset:128
	global_load_dwordx4 v[230:233], v238, s[98:99] offset:128
	global_load_dwordx4 v[166:169], v206, s[100:101] offset:128
	global_load_dwordx4 v[170:173], v207, s[100:101] offset:128
	global_load_dwordx4 v[174:177], v208, s[100:101] offset:128
	global_load_dwordx4 v[190:193], v238, s[100:101] offset:128
	s_add_u32 s98, s98, 0x100
	s_addc_u32 s99, s99, 0
	s_add_u32 s100, s100, 0x100
	s_addc_u32 s101, s101, 0
	global_load_dwordx4 v[66:69], v206, s[98:99]
	global_load_dwordx4 v[70:73], v207, s[98:99]
	global_load_dwordx4 v[74:77], v208, s[98:99]
	global_load_dwordx4 v[78:81], v238, s[98:99]
	global_load_dwordx4 v[82:85], v206, s[100:101]
	global_load_dwordx4 v[86:89], v207, s[100:101]
	global_load_dwordx4 v[90:93], v208, s[100:101]
	global_load_dwordx4 v[94:97], v238, s[100:101]
	v_lshrrev_b32_e32 v239, 3, v165
	v_and_b32_e32 v0, 7, v165
	v_mul_u32_u24_e32 v180, 0x90, v239
	v_lshl_add_u32 v180, v0, 4, v180
	v_and_b32_e32 v239, 31, v165
	v_bfe_u32 v0, v165, 5, 1
	v_lshrrev_b32_e32 v179, 8, v165
	v_lshl_or_b32 v178, v179, 7, v239
	v_mul_u32_u24_e32 v178, 0x90, v178
	v_lshl_add_u32 v178, v0, 4, v178
	v_bfe_u32 v179, v165, 6, 2
	v_lshl_or_b32 v179, v179, 6, v239
	v_mul_u32_u24_e32 v179, 0x90, v179
	v_lshl_add_u32 v179, v0, 4, v179
	s_mov_b32 s12, 0x12000
	s_mov_b32 s13, 9
	s_barrier
	s_waitcnt vmcnt(23)
	ds_write_b128 v180, v[130:133]
	s_waitcnt vmcnt(22)
	ds_write_b128 v180, v[134:137] offset:9216
	s_waitcnt vmcnt(21)
	ds_write_b128 v180, v[138:141] offset:18432
	s_waitcnt vmcnt(20)
	ds_write_b128 v180, v[142:145] offset:27648
	s_waitcnt vmcnt(19)
	ds_write_b128 v180, v[146:149] offset:36864
	s_waitcnt vmcnt(18)
	ds_write_b128 v180, v[150:153] offset:46080
	s_waitcnt vmcnt(17)
	ds_write_b128 v180, v[154:157] offset:55296
	s_waitcnt vmcnt(16)
	ds_write_b128 v180, v[158:161] offset:64512
	v_add_u32_e32 v180, 0x12000, v180
	s_waitcnt vmcnt(15)
	ds_write_b128 v180, v[218:221]
	s_waitcnt vmcnt(14)
	ds_write_b128 v180, v[222:225] offset:9216
	s_waitcnt vmcnt(13)
	ds_write_b128 v180, v[226:229] offset:18432
	s_waitcnt vmcnt(12)
	ds_write_b128 v180, v[230:233] offset:27648
	s_waitcnt vmcnt(11)
	ds_write_b128 v180, v[166:169] offset:36864
	s_waitcnt vmcnt(10)
	ds_write_b128 v180, v[170:173] offset:46080
	s_waitcnt vmcnt(9)
	ds_write_b128 v180, v[174:177] offset:55296
	s_waitcnt vmcnt(8)
	ds_write_b128 v180, v[190:193] offset:64512
	s_waitcnt vmcnt(0)
	v_mov_b64_e32 v[130:131], v[66:67]
	v_mov_b64_e32 v[132:133], v[68:69]
	v_mov_b64_e32 v[134:135], v[70:71]
	v_mov_b64_e32 v[136:137], v[72:73]
	v_mov_b64_e32 v[138:139], v[74:75]
	v_mov_b64_e32 v[140:141], v[76:77]
	v_mov_b64_e32 v[142:143], v[78:79]
	v_mov_b64_e32 v[144:145], v[80:81]
	v_mov_b64_e32 v[146:147], v[82:83]
	v_mov_b64_e32 v[148:149], v[84:85]
	v_mov_b64_e32 v[150:151], v[86:87]
	v_mov_b64_e32 v[152:153], v[88:89]
	v_mov_b64_e32 v[154:155], v[90:91]
	v_mov_b64_e32 v[156:157], v[92:93]
	v_mov_b64_e32 v[158:159], v[94:95]
	v_mov_b64_e32 v[160:161], v[96:97]
	s_waitcnt lgkmcnt(0)
	s_branch .Lg3_k_m0
.Lg3_start_m0:
	v_lshrrev_b32_e32 v239, 3, v165
	v_and_b32_e32 v0, 7, v165
	v_mul_u32_u24_e32 v180, 0x90, v239
	v_lshl_add_u32 v180, v0, 4, v180
	v_and_b32_e32 v239, 31, v165
	v_bfe_u32 v0, v165, 5, 1
	v_lshrrev_b32_e32 v179, 8, v165
	v_lshl_or_b32 v178, v179, 7, v239
	v_mul_u32_u24_e32 v178, 0x90, v178
	v_lshl_add_u32 v178, v0, 4, v178
	v_bfe_u32 v179, v165, 6, 2
	v_lshl_or_b32 v179, v179, 6, v239
	v_mul_u32_u24_e32 v179, 0x90, v179
	v_lshl_add_u32 v179, v0, 4, v179
	s_mov_b32 s12, 0x12000
	s_mov_b32 s13, 9
	s_barrier
	s_waitcnt vmcnt(34)
	ds_write_b128 v180, v[130:133]
	s_waitcnt vmcnt(33)
	ds_write_b128 v180, v[134:137] offset:9216
	s_waitcnt vmcnt(32)
	ds_write_b128 v180, v[138:141] offset:18432
	s_waitcnt vmcnt(31)
	ds_write_b128 v180, v[142:145] offset:27648
	s_waitcnt vmcnt(30)
	ds_write_b128 v180, v[146:149] offset:36864
	s_waitcnt vmcnt(29)
	ds_write_b128 v180, v[150:153] offset:46080
	s_waitcnt vmcnt(28)
	ds_write_b128 v180, v[154:157] offset:55296
	s_waitcnt vmcnt(27)
	ds_write_b128 v180, v[158:161] offset:64512
	v_add_u32_e32 v180, 0x12000, v180
	s_waitcnt vmcnt(26)
	ds_write_b128 v180, v[218:221]
	s_waitcnt vmcnt(25)
	ds_write_b128 v180, v[222:225] offset:9216
	s_waitcnt vmcnt(24)
	ds_write_b128 v180, v[226:229] offset:18432
	s_waitcnt vmcnt(23)
	ds_write_b128 v180, v[230:233] offset:27648
	s_waitcnt vmcnt(22)
	ds_write_b128 v180, v[166:169] offset:36864
	s_waitcnt vmcnt(21)
	ds_write_b128 v180, v[170:173] offset:46080
	s_waitcnt vmcnt(20)
	ds_write_b128 v180, v[174:177] offset:55296
	s_waitcnt vmcnt(19)
	ds_write_b128 v180, v[190:193] offset:64512
	s_waitcnt vmcnt(11)
	v_mov_b64_e32 v[130:131], v[66:67]
	v_mov_b64_e32 v[132:133], v[68:69]
	v_mov_b64_e32 v[134:135], v[70:71]
	v_mov_b64_e32 v[136:137], v[72:73]
	v_mov_b64_e32 v[138:139], v[74:75]
	v_mov_b64_e32 v[140:141], v[76:77]
	v_mov_b64_e32 v[142:143], v[78:79]
	v_mov_b64_e32 v[144:145], v[80:81]
	v_mov_b64_e32 v[146:147], v[82:83]
	v_mov_b64_e32 v[148:149], v[84:85]
	v_mov_b64_e32 v[150:151], v[86:87]
	v_mov_b64_e32 v[152:153], v[88:89]
	v_mov_b64_e32 v[154:155], v[90:91]
	v_mov_b64_e32 v[156:157], v[92:93]
	v_mov_b64_e32 v[158:159], v[94:95]
	v_mov_b64_e32 v[160:161], v[96:97]
	s_waitcnt lgkmcnt(0)
; #define G5_LOAD(k0)                                                                 \
;   {                                                                                 \
;     _Pragma("unroll") for (int i_ = 0; i_ < 4; ++i_) ra[i_] = ldg16(Ap + (size_t)(i_ * 64) * lda + (k0)); \
;     _Pragma("unroll") for (int i_ = 0; i_ < 4; ++i_) rb[i_] = ldg16(Bp + (size_t)(i_ * 64) * ldb + (k0)); \
;   }
; #define G5_STORE(s)                                                                 \
;   {                                                                                 \
;     _Pragma("unroll") for (int i_ = 0; i_ < 4; ++i_) *(u32x4*)(Sw + (s) * STG + i_ * 64 * GS) = ra[i_]; \
;     _Pragma("unroll") for (int i_ = 0; i_ < 4; ++i_) *(u32x4*)(Sw + (s) * STG + 256 * GS + i_ * 64 * GS) = rb[i_]; \
;   }
; template <typename Epi>
; DI void gemm_tile512(const u16* __restrict__ A, int lda, const u16* __restrict__ Bt, int ldb, int K, char* lds_all, Epi epi) {
;     ...
;   const int nk = K >> 6;
;   __syncthreads();
;   G5_LOAD(0);
;   G5_STORE(0);
;   G5_LOAD(64);
;   __syncthreads();
;   for (int kt = 0; kt + 2 < nk; ++kt) {
;     const int cur = kt & 1;
;     G5_COMPUTE(cur);
;     G5_STORE(cur ^ 1);
;     G5_LOAD((kt + 2) << 6);
;     __syncthreads();
;   }
.Lg3_k_m0:
	s_barrier
	ds_read_b128 v[194:197], v179 offset:36864
	ds_read_b128 v[166:169], v178
	ds_read_b128 v[198:201], v179 offset:41472
	ds_read_b128 v[170:173], v178 offset:4608
	ds_read_b128 v[174:177], v178 offset:9216
	ds_read_b128 v[190:193], v178 offset:13824
	s_waitcnt lgkmcnt(4)
	v_mfma_f32_32x32x16_bf16 v[114:129], v[194:197], v[166:169], 0
	ds_read_b128 v[234:237], v179 offset:36896
	s_waitcnt lgkmcnt(4)
	v_mfma_f32_32x32x16_bf16 v[98:113], v[198:201], v[166:169], 0
	ds_read_b128 v[218:221], v178 offset:32
	s_waitcnt lgkmcnt(4)
	v_mfma_f32_32x32x16_bf16 v[82:97], v[194:197], v[170:173], 0
	ds_read_b128 v[202:205], v179 offset:41504
	v_mfma_f32_32x32x16_bf16 v[66:81], v[198:201], v[170:173], 0
	ds_read_b128 v[222:225], v178 offset:4640
	s_waitcnt lgkmcnt(5)
	v_mfma_f32_32x32x16_bf16 v[50:65], v[194:197], v[174:177], 0
	ds_read_b128 v[226:229], v178 offset:9248
	v_mfma_f32_32x32x16_bf16 v[34:49], v[198:201], v[174:177], 0
	ds_read_b128 v[230:233], v178 offset:13856
	s_waitcnt lgkmcnt(6)
	v_mfma_f32_32x32x16_bf16 v[18:33], v[194:197], v[190:193], 0
	v_mfma_f32_32x32x16_bf16 v[2:17], v[198:201], v[190:193], 0
	s_waitcnt lgkmcnt(4)
	v_mfma_f32_32x32x16_bf16 v[114:129], v[234:237], v[218:221], v[114:129]
	ds_read_b128 v[194:197], v179 offset:36928
	s_waitcnt lgkmcnt(4)
	v_mfma_f32_32x32x16_bf16 v[98:113], v[202:205], v[218:221], v[98:113]
	ds_read_b128 v[166:169], v178 offset:64
	s_waitcnt lgkmcnt(4)
	v_mfma_f32_32x32x16_bf16 v[82:97], v[234:237], v[222:225], v[82:97]
	ds_read_b128 v[198:201], v179 offset:41536
	v_mfma_f32_32x32x16_bf16 v[66:81], v[202:205], v[222:225], v[66:81]
	ds_read_b128 v[170:173], v178 offset:4672
	s_waitcnt lgkmcnt(5)
	v_mfma_f32_32x32x16_bf16 v[50:65], v[234:237], v[226:229], v[50:65]
	ds_read_b128 v[174:177], v178 offset:9280
	v_mfma_f32_32x32x16_bf16 v[34:49], v[202:205], v[226:229], v[34:49]
	ds_read_b128 v[190:193], v178 offset:13888
	s_waitcnt lgkmcnt(6)
	v_mfma_f32_32x32x16_bf16 v[18:33], v[234:237], v[230:233], v[18:33]
	v_mfma_f32_32x32x16_bf16 v[2:17], v[202:205], v[230:233], v[2:17]
	s_cmp_eq_u32 s32, 0
	s_cbranch_scc1 .Lg3_nd0_m0
	global_store_dwordx4 v253, v[182:185], s[50:51]
	v_add_u32_e32 v253, 0x16000, v253
.Lg3_nd0_m0:
	v_subrev_u32_e32 v180, s12, v180
	s_waitcnt lgkmcnt(4)
	v_mfma_f32_32x32x16_bf16 v[114:129], v[194:197], v[166:169], v[114:129]
	ds_read_b128 v[234:237], v179 offset:36960
	s_waitcnt lgkmcnt(4)
	v_mfma_f32_32x32x16_bf16 v[98:113], v[198:201], v[166:169], v[98:113]
	ds_read_b128 v[218:221], v178 offset:96
	s_waitcnt lgkmcnt(4)
	v_mfma_f32_32x32x16_bf16 v[82:97], v[194:197], v[170:173], v[82:97]
	ds_read_b128 v[202:205], v179 offset:41568
	v_mfma_f32_32x32x16_bf16 v[66:81], v[198:201], v[170:173], v[66:81]
	ds_read_b128 v[222:225], v178 offset:4704
	s_waitcnt lgkmcnt(5)
	v_mfma_f32_32x32x16_bf16 v[50:65], v[194:197], v[174:177], v[50:65]
	ds_read_b128 v[226:229], v178 offset:9312
	v_mfma_f32_32x32x16_bf16 v[34:49], v[198:201], v[174:177], v[34:49]
	ds_read_b128 v[230:233], v178 offset:13920
	v_add_u32_e32 v178, s12, v178
	v_add_u32_e32 v179, s12, v179
	s_waitcnt lgkmcnt(6)
	v_mfma_f32_32x32x16_bf16 v[18:33], v[194:197], v[190:193], v[18:33]
	v_mfma_f32_32x32x16_bf16 v[2:17], v[198:201], v[190:193], v[2:17]
	s_sub_u32 s12, 0, s12
	s_add_u32 s98, s98, 0x80
	s_addc_u32 s99, s99, 0
	s_add_u32 s100, s100, 0x80
	s_addc_u32 s101, s101, 0
	s_waitcnt lgkmcnt(0)
	s_barrier
	ds_read_b128 v[194:197], v179 offset:36864
	ds_read_b128 v[166:169], v178
	v_mfma_f32_32x32x16_bf16 v[114:129], v[234:237], v[218:221], v[114:129]
	ds_read_b128 v[198:201], v179 offset:41472
	v_mfma_f32_32x32x16_bf16 v[98:113], v[202:205], v[218:221], v[98:113]
	ds_read_b128 v[170:173], v178 offset:4608
	v_mfma_f32_32x32x16_bf16 v[82:97], v[234:237], v[222:225], v[82:97]
	ds_read_b128 v[174:177], v178 offset:9216
	v_mfma_f32_32x32x16_bf16 v[66:81], v[202:205], v[222:225], v[66:81]
	ds_read_b128 v[190:193], v178 offset:13824
	v_mfma_f32_32x32x16_bf16 v[50:65], v[234:237], v[226:229], v[50:65]
	v_mfma_f32_32x32x16_bf16 v[34:49], v[202:205], v[226:229], v[34:49]
	v_mfma_f32_32x32x16_bf16 v[18:33], v[234:237], v[230:233], v[18:33]
	v_mfma_f32_32x32x16_bf16 v[2:17], v[202:205], v[230:233], v[2:17]
	s_waitcnt lgkmcnt(4)
	v_mfma_f32_32x32x16_bf16 v[114:129], v[194:197], v[166:169], v[114:129]
	ds_read_b128 v[234:237], v179 offset:36896
	s_waitcnt lgkmcnt(4)
	v_mfma_f32_32x32x16_bf16 v[98:113], v[198:201], v[166:169], v[98:113]
	ds_read_b128 v[218:221], v178 offset:32
	ds_write_b128 v180, v[130:133]
	global_load_dwordx4 v[130:133], v206, s[98:99]
	s_waitcnt lgkmcnt(5)
	v_mfma_f32_32x32x16_bf16 v[82:97], v[194:197], v[170:173], v[82:97]
	ds_read_b128 v[202:205], v179 offset:41504
	v_mfma_f32_32x32x16_bf16 v[66:81], v[198:201], v[170:173], v[66:81]
	ds_read_b128 v[222:225], v178 offset:4640
	ds_write_b128 v180, v[134:137] offset:9216
	global_load_dwordx4 v[134:137], v207, s[98:99]
	s_waitcnt lgkmcnt(7)
	v_mfma_f32_32x32x16_bf16 v[50:65], v[194:197], v[174:177], v[50:65]
	ds_read_b128 v[226:229], v178 offset:9248
	v_mfma_f32_32x32x16_bf16 v[34:49], v[198:201], v[174:177], v[34:49]
	ds_read_b128 v[230:233], v178 offset:13856
	ds_write_b128 v180, v[138:141] offset:18432
	global_load_dwordx4 v[138:141], v208, s[98:99]
	s_waitcnt lgkmcnt(9)
	v_mfma_f32_32x32x16_bf16 v[18:33], v[194:197], v[190:193], v[18:33]
	v_mfma_f32_32x32x16_bf16 v[2:17], v[198:201], v[190:193], v[2:17]
	ds_write_b128 v180, v[142:145] offset:27648
	global_load_dwordx4 v[142:145], v238, s[98:99]
	s_waitcnt lgkmcnt(8)
	v_mfma_f32_32x32x16_bf16 v[114:129], v[234:237], v[218:221], v[114:129]
	ds_read_b128 v[194:197], v179 offset:36928
	s_waitcnt lgkmcnt(7)
	v_mfma_f32_32x32x16_bf16 v[98:113], v[202:205], v[218:221], v[98:113]
	ds_read_b128 v[166:169], v178 offset:64
	ds_write_b128 v180, v[146:149] offset:36864
	global_load_dwordx4 v[146:149], v206, s[100:101]
	s_waitcnt lgkmcnt(8)
	v_mfma_f32_32x32x16_bf16 v[82:97], v[234:237], v[222:225], v[82:97]
	ds_read_b128 v[198:201], v179 offset:41536
	v_mfma_f32_32x32x16_bf16 v[66:81], v[202:205], v[222:225], v[66:81]
	ds_read_b128 v[170:173], v178 offset:4672
	ds_write_b128 v180, v[150:153] offset:46080
	global_load_dwordx4 v[150:153], v207, s[100:101]
	s_waitcnt lgkmcnt(9)
	v_mfma_f32_32x32x16_bf16 v[50:65], v[234:237], v[226:229], v[50:65]
	ds_read_b128 v[174:177], v178 offset:9280
	v_mfma_f32_32x32x16_bf16 v[34:49], v[202:205], v[226:229], v[34:49]
	ds_read_b128 v[190:193], v178 offset:13888
	ds_write_b128 v180, v[154:157] offset:55296
	global_load_dwordx4 v[154:157], v208, s[100:101]
	s_waitcnt lgkmcnt(11)
	v_mfma_f32_32x32x16_bf16 v[18:33], v[234:237], v[230:233], v[18:33]
	v_mfma_f32_32x32x16_bf16 v[2:17], v[202:205], v[230:233], v[2:17]
	ds_write_b128 v180, v[158:161] offset:64512
	global_load_dwordx4 v[158:161], v238, s[100:101]
	s_cmp_eq_u32 s32, 0
	s_cbranch_scc1 .Lg3_nd1_m0
	global_store_dwordx4 v253, v[186:189], s[50:51]
	v_add_u32_e32 v253, 0x16000, v253
; #define G5_LOAD(k0)                                                                 \
;   {                                                                                 \
;     _Pragma("unroll") for (int i_ = 0; i_ < 4; ++i_) ra[i_] = ldg16(Ap + (size_t)(i_ * 64) * lda + (k0)); \
;     _Pragma("unroll") for (int i_ = 0; i_ < 4; ++i_) rb[i_] = ldg16(Bp + (size_t)(i_ * 64) * ldb + (k0)); \
;   }
; #define G5_STORE(s)                                                                 \
;   {                                                                                 \
;     _Pragma("unroll") for (int i_ = 0; i_ < 4; ++i_) *(u32x4*)(Sw + (s) * STG + i_ * 64 * GS) = ra[i_]; \
;     _Pragma("unroll") for (int i_ = 0; i_ < 4; ++i_) *(u32x4*)(Sw + (s) * STG + 256 * GS + i_ * 64 * GS) = rb[i_]; \
;   }
; template <typename Epi>
; DI void gemm_tile512(const u16* __restrict__ A, int lda, const u16* __restrict__ Bt, int ldb, int K, char* lds_all, Epi epi) {
;     ...
;   const int nk = K >> 6;
;   __syncthreads();
;   G5_LOAD(0);
;   G5_STORE(0);
;   G5_LOAD(64);
;   __syncthreads();
;   for (int kt = 0; kt + 2 < nk; ++kt) {
;     const int cur = kt & 1;
;     G5_COMPUTE(cur);
;     G5_STORE(cur ^ 1);
;     G5_LOAD((kt + 2) << 6);
;     __syncthreads();
;   }
.Lg3_nd1_m0:
	v_subrev_u32_e32 v180, s12, v180
	s_waitcnt lgkmcnt(8)
	v_mfma_f32_32x32x16_bf16 v[114:129], v[194:197], v[166:169], v[114:129]
	ds_read_b128 v[234:237], v179 offset:36960
	s_waitcnt lgkmcnt(7)
	v_mfma_f32_32x32x16_bf16 v[98:113], v[198:201], v[166:169], v[98:113]
	ds_read_b128 v[218:221], v178 offset:96
	s_waitcnt lgkmcnt(7)
	v_mfma_f32_32x32x16_bf16 v[82:97], v[194:197], v[170:173], v[82:97]
	ds_read_b128 v[202:205], v179 offset:41568
	v_mfma_f32_32x32x16_bf16 v[66:81], v[198:201], v[170:173], v[66:81]
	ds_read_b128 v[222:225], v178 offset:4704
	s_waitcnt lgkmcnt(7)
	v_mfma_f32_32x32x16_bf16 v[50:65], v[194:197], v[174:177], v[50:65]
	ds_read_b128 v[226:229], v178 offset:9312
	v_mfma_f32_32x32x16_bf16 v[34:49], v[198:201], v[174:177], v[34:49]
	ds_read_b128 v[230:233], v178 offset:13920
	v_add_u32_e32 v178, s12, v178
	v_add_u32_e32 v179, s12, v179
	s_waitcnt lgkmcnt(8)
	v_mfma_f32_32x32x16_bf16 v[18:33], v[194:197], v[190:193], v[18:33]
	v_mfma_f32_32x32x16_bf16 v[2:17], v[198:201], v[190:193], v[2:17]
	s_sub_u32 s12, 0, s12
	s_add_u32 s98, s98, 0x80
	s_addc_u32 s99, s99, 0
	s_add_u32 s100, s100, 0x80
	s_addc_u32 s101, s101, 0
	s_waitcnt lgkmcnt(0)
	s_barrier
	ds_read_b128 v[194:197], v179 offset:36864
	ds_read_b128 v[166:169], v178
	v_mfma_f32_32x32x16_bf16 v[114:129], v[234:237], v[218:221], v[114:129]
	ds_read_b128 v[198:201], v179 offset:41472
	v_mfma_f32_32x32x16_bf16 v[98:113], v[202:205], v[218:221], v[98:113]
	ds_read_b128 v[170:173], v178 offset:4608
	v_mfma_f32_32x32x16_bf16 v[82:97], v[234:237], v[222:225], v[82:97]
	ds_read_b128 v[174:177], v178 offset:9216
	v_mfma_f32_32x32x16_bf16 v[66:81], v[202:205], v[222:225], v[66:81]
	ds_read_b128 v[190:193], v178 offset:13824
	v_mfma_f32_32x32x16_bf16 v[50:65], v[234:237], v[226:229], v[50:65]
	v_mfma_f32_32x32x16_bf16 v[34:49], v[202:205], v[226:229], v[34:49]
	v_mfma_f32_32x32x16_bf16 v[18:33], v[234:237], v[230:233], v[18:33]
	v_mfma_f32_32x32x16_bf16 v[2:17], v[202:205], v[230:233], v[2:17]
	s_waitcnt lgkmcnt(4)
	v_mfma_f32_32x32x16_bf16 v[114:129], v[194:197], v[166:169], v[114:129]
	ds_read_b128 v[234:237], v179 offset:36896
	s_waitcnt lgkmcnt(4)
	v_mfma_f32_32x32x16_bf16 v[98:113], v[198:201], v[166:169], v[98:113]
	ds_read_b128 v[218:221], v178 offset:32
	s_waitcnt vmcnt(7)
	ds_write_b128 v180, v[130:133]
	global_load_dwordx4 v[130:133], v206, s[98:99]
	s_waitcnt lgkmcnt(5)
	v_mfma_f32_32x32x16_bf16 v[82:97], v[194:197], v[170:173], v[82:97]
	ds_read_b128 v[202:205], v179 offset:41504
	v_mfma_f32_32x32x16_bf16 v[66:81], v[198:201], v[170:173], v[66:81]
	ds_read_b128 v[222:225], v178 offset:4640
	s_waitcnt vmcnt(7)
	ds_write_b128 v180, v[134:137] offset:9216
	global_load_dwordx4 v[134:137], v207, s[98:99]
	s_waitcnt lgkmcnt(7)
	v_mfma_f32_32x32x16_bf16 v[50:65], v[194:197], v[174:177], v[50:65]
	ds_read_b128 v[226:229], v178 offset:9248
	v_mfma_f32_32x32x16_bf16 v[34:49], v[198:201], v[174:177], v[34:49]
	ds_read_b128 v[230:233], v178 offset:13856
	s_waitcnt vmcnt(7)
	ds_write_b128 v180, v[138:141] offset:18432
	global_load_dwordx4 v[138:141], v208, s[98:99]
	s_waitcnt lgkmcnt(9)
	v_mfma_f32_32x32x16_bf16 v[18:33], v[194:197], v[190:193], v[18:33]
	v_mfma_f32_32x32x16_bf16 v[2:17], v[198:201], v[190:193], v[2:17]
	s_waitcnt vmcnt(7)
	ds_write_b128 v180, v[142:145] offset:27648
	global_load_dwordx4 v[142:145], v238, s[98:99]
	s_waitcnt lgkmcnt(8)
	v_mfma_f32_32x32x16_bf16 v[114:129], v[234:237], v[218:221], v[114:129]
	ds_read_b128 v[194:197], v179 offset:36928
	s_waitcnt lgkmcnt(7)
	v_mfma_f32_32x32x16_bf16 v[98:113], v[202:205], v[218:221], v[98:113]
	ds_read_b128 v[166:169], v178 offset:64
	s_waitcnt vmcnt(7)
	ds_write_b128 v180, v[146:149] offset:36864
	global_load_dwordx4 v[146:149], v206, s[100:101]
	s_waitcnt lgkmcnt(8)
	v_mfma_f32_32x32x16_bf16 v[82:97], v[234:237], v[222:225], v[82:97]
	ds_read_b128 v[198:201], v179 offset:41536
	v_mfma_f32_32x32x16_bf16 v[66:81], v[202:205], v[222:225], v[66:81]
	ds_read_b128 v[170:173], v178 offset:4672
	s_waitcnt vmcnt(7)
	ds_write_b128 v180, v[150:153] offset:46080
	global_load_dwordx4 v[150:153], v207, s[100:101]
	s_waitcnt lgkmcnt(9)
	v_mfma_f32_32x32x16_bf16 v[50:65], v[234:237], v[226:229], v[50:65]
	ds_read_b128 v[174:177], v178 offset:9280
	v_mfma_f32_32x32x16_bf16 v[34:49], v[202:205], v[226:229], v[34:49]
	ds_read_b128 v[190:193], v178 offset:13888
	s_waitcnt vmcnt(7)
	ds_write_b128 v180, v[154:157] offset:55296
	global_load_dwordx4 v[154:157], v208, s[100:101]
	s_waitcnt lgkmcnt(11)
	v_mfma_f32_32x32x16_bf16 v[18:33], v[234:237], v[230:233], v[18:33]
	v_mfma_f32_32x32x16_bf16 v[2:17], v[202:205], v[230:233], v[2:17]
	s_waitcnt vmcnt(7)
	ds_write_b128 v180, v[158:161] offset:64512
	global_load_dwordx4 v[158:161], v238, s[100:101]
	s_cmp_eq_u32 s32, 0
	s_cbranch_scc1 .Lg3_nd2_m0
	global_store_dwordx4 v253, v[210:213], s[50:51]
	v_add_u32_e32 v253, 0x16000, v253
; #define G5_LOAD(k0)                                                                 \
;   {                                                                                 \
;     _Pragma("unroll") for (int i_ = 0; i_ < 4; ++i_) ra[i_] = ldg16(Ap + (size_t)(i_ * 64) * lda + (k0)); \
;     _Pragma("unroll") for (int i_ = 0; i_ < 4; ++i_) rb[i_] = ldg16(Bp + (size_t)(i_ * 64) * ldb + (k0)); \
;   }
; #define G5_STORE(s)                                                                 \
;   {                                                                                 \
;     _Pragma("unroll") for (int i_ = 0; i_ < 4; ++i_) *(u32x4*)(Sw + (s) * STG + i_ * 64 * GS) = ra[i_]; \
;     _Pragma("unroll") for (int i_ = 0; i_ < 4; ++i_) *(u32x4*)(Sw + (s) * STG + 256 * GS + i_ * 64 * GS) = rb[i_]; \
;   }
; template <typename Epi>
; DI void gemm_tile512(const u16* __restrict__ A, int lda, const u16* __restrict__ Bt, int ldb, int K, char* lds_all, Epi epi) {
;     ...
;   const int nk = K >> 6;
;   __syncthreads();
;   G5_LOAD(0);
;   G5_STORE(0);
;   G5_LOAD(64);
;   __syncthreads();
;   for (int kt = 0; kt + 2 < nk; ++kt) {
;     const int cur = kt & 1;
;     G5_COMPUTE(cur);
;     G5_STORE(cur ^ 1);
;     G5_LOAD((kt + 2) << 6);
;     __syncthreads();
;   }
.Lg3_nd2_m0:
	v_subrev_u32_e32 v180, s12, v180
	s_waitcnt lgkmcnt(8)
	v_mfma_f32_32x32x16_bf16 v[114:129], v[194:197], v[166:169], v[114:129]
	ds_read_b128 v[234:237], v179 offset:36960
	s_waitcnt lgkmcnt(7)
	v_mfma_f32_32x32x16_bf16 v[98:113], v[198:201], v[166:169], v[98:113]
	ds_read_b128 v[218:221], v178 offset:96
	s_waitcnt lgkmcnt(7)
	v_mfma_f32_32x32x16_bf16 v[82:97], v[194:197], v[170:173], v[82:97]
	ds_read_b128 v[202:205], v179 offset:41568
	v_mfma_f32_32x32x16_bf16 v[66:81], v[198:201], v[170:173], v[66:81]
	ds_read_b128 v[222:225], v178 offset:4704
	s_waitcnt lgkmcnt(7)
	v_mfma_f32_32x32x16_bf16 v[50:65], v[194:197], v[174:177], v[50:65]
	ds_read_b128 v[226:229], v178 offset:9312
	v_mfma_f32_32x32x16_bf16 v[34:49], v[198:201], v[174:177], v[34:49]
	ds_read_b128 v[230:233], v178 offset:13920
	v_add_u32_e32 v178, s12, v178
	v_add_u32_e32 v179, s12, v179
	s_waitcnt lgkmcnt(8)
	v_mfma_f32_32x32x16_bf16 v[18:33], v[194:197], v[190:193], v[18:33]
	v_mfma_f32_32x32x16_bf16 v[2:17], v[198:201], v[190:193], v[2:17]
	s_sub_u32 s12, 0, s12
	s_add_u32 s98, s98, 0x80
	s_addc_u32 s99, s99, 0
	s_add_u32 s100, s100, 0x80
	s_addc_u32 s101, s101, 0
	s_waitcnt lgkmcnt(0)
	s_barrier
	ds_read_b128 v[194:197], v179 offset:36864
	ds_read_b128 v[166:169], v178
	v_mfma_f32_32x32x16_bf16 v[114:129], v[234:237], v[218:221], v[114:129]
	ds_read_b128 v[198:201], v179 offset:41472
	v_mfma_f32_32x32x16_bf16 v[98:113], v[202:205], v[218:221], v[98:113]
	ds_read_b128 v[170:173], v178 offset:4608
	v_mfma_f32_32x32x16_bf16 v[82:97], v[234:237], v[222:225], v[82:97]
	ds_read_b128 v[174:177], v178 offset:9216
	v_mfma_f32_32x32x16_bf16 v[66:81], v[202:205], v[222:225], v[66:81]
	ds_read_b128 v[190:193], v178 offset:13824
	v_mfma_f32_32x32x16_bf16 v[50:65], v[234:237], v[226:229], v[50:65]
	v_mfma_f32_32x32x16_bf16 v[34:49], v[202:205], v[226:229], v[34:49]
	v_mfma_f32_32x32x16_bf16 v[18:33], v[234:237], v[230:233], v[18:33]
	v_mfma_f32_32x32x16_bf16 v[2:17], v[202:205], v[230:233], v[2:17]
	s_waitcnt lgkmcnt(4)
	v_mfma_f32_32x32x16_bf16 v[114:129], v[194:197], v[166:169], v[114:129]
	ds_read_b128 v[234:237], v179 offset:36896
	s_waitcnt lgkmcnt(4)
	v_mfma_f32_32x32x16_bf16 v[98:113], v[198:201], v[166:169], v[98:113]
	ds_read_b128 v[218:221], v178 offset:32
	s_waitcnt vmcnt(7)
	ds_write_b128 v180, v[130:133]
	global_load_dwordx4 v[130:133], v206, s[98:99]
	s_waitcnt lgkmcnt(5)
	v_mfma_f32_32x32x16_bf16 v[82:97], v[194:197], v[170:173], v[82:97]
	ds_read_b128 v[202:205], v179 offset:41504
	v_mfma_f32_32x32x16_bf16 v[66:81], v[198:201], v[170:173], v[66:81]
	ds_read_b128 v[222:225], v178 offset:4640
	s_waitcnt vmcnt(7)
	ds_write_b128 v180, v[134:137] offset:9216
	global_load_dwordx4 v[134:137], v207, s[98:99]
	s_waitcnt lgkmcnt(7)
	v_mfma_f32_32x32x16_bf16 v[50:65], v[194:197], v[174:177], v[50:65]
	ds_read_b128 v[226:229], v178 offset:9248
	v_mfma_f32_32x32x16_bf16 v[34:49], v[198:201], v[174:177], v[34:49]
	ds_read_b128 v[230:233], v178 offset:13856
	s_waitcnt vmcnt(7)
	ds_write_b128 v180, v[138:141] offset:18432
	global_load_dwordx4 v[138:141], v208, s[98:99]
	s_waitcnt lgkmcnt(9)
	v_mfma_f32_32x32x16_bf16 v[18:33], v[194:197], v[190:193], v[18:33]
	v_mfma_f32_32x32x16_bf16 v[2:17], v[198:201], v[190:193], v[2:17]
	s_waitcnt vmcnt(7)
	ds_write_b128 v180, v[142:145] offset:27648
	global_load_dwordx4 v[142:145], v238, s[98:99]
	s_waitcnt lgkmcnt(8)
	v_mfma_f32_32x32x16_bf16 v[114:129], v[234:237], v[218:221], v[114:129]
	ds_read_b128 v[194:197], v179 offset:36928
	s_waitcnt lgkmcnt(7)
	v_mfma_f32_32x32x16_bf16 v[98:113], v[202:205], v[218:221], v[98:113]
	ds_read_b128 v[166:169], v178 offset:64
	s_waitcnt vmcnt(7)
	ds_write_b128 v180, v[146:149] offset:36864
	global_load_dwordx4 v[146:149], v206, s[100:101]
	s_waitcnt lgkmcnt(8)
	v_mfma_f32_32x32x16_bf16 v[82:97], v[234:237], v[222:225], v[82:97]
	ds_read_b128 v[198:201], v179 offset:41536
	v_mfma_f32_32x32x16_bf16 v[66:81], v[202:205], v[222:225], v[66:81]
	ds_read_b128 v[170:173], v178 offset:4672
	s_waitcnt vmcnt(7)
	ds_write_b128 v180, v[150:153] offset:46080
	global_load_dwordx4 v[150:153], v207, s[100:101]
	s_waitcnt lgkmcnt(9)
	v_mfma_f32_32x32x16_bf16 v[50:65], v[234:237], v[226:229], v[50:65]
	ds_read_b128 v[174:177], v178 offset:9280
	v_mfma_f32_32x32x16_bf16 v[34:49], v[202:205], v[226:229], v[34:49]
	ds_read_b128 v[190:193], v178 offset:13888
	s_waitcnt vmcnt(7)
	ds_write_b128 v180, v[154:157] offset:55296
	global_load_dwordx4 v[154:157], v208, s[100:101]
	s_waitcnt lgkmcnt(11)
	v_mfma_f32_32x32x16_bf16 v[18:33], v[234:237], v[230:233], v[18:33]
	v_mfma_f32_32x32x16_bf16 v[2:17], v[202:205], v[230:233], v[2:17]
	s_waitcnt vmcnt(7)
	ds_write_b128 v180, v[158:161] offset:64512
	global_load_dwordx4 v[158:161], v238, s[100:101]
	s_cmp_eq_u32 s32, 0
	s_cbranch_scc1 .Lg3_nd3_m0
	global_store_dwordx4 v253, v[240:243], s[50:51]
	v_add_u32_e32 v253, 0x16000, v253
; #define G5_LOAD(k0)                                                                 \
;   {                                                                                 \
;     _Pragma("unroll") for (int i_ = 0; i_ < 4; ++i_) ra[i_] = ldg16(Ap + (size_t)(i_ * 64) * lda + (k0)); \
;     _Pragma("unroll") for (int i_ = 0; i_ < 4; ++i_) rb[i_] = ldg16(Bp + (size_t)(i_ * 64) * ldb + (k0)); \
;   }
; #define G5_STORE(s)                                                                 \
;   {                                                                                 \
;     _Pragma("unroll") for (int i_ = 0; i_ < 4; ++i_) *(u32x4*)(Sw + (s) * STG + i_ * 64 * GS) = ra[i_]; \
;     _Pragma("unroll") for (int i_ = 0; i_ < 4; ++i_) *(u32x4*)(Sw + (s) * STG + 256 * GS + i_ * 64 * GS) = rb[i_]; \
;   }
; template <typename Epi>
; DI void gemm_tile512(const u16* __restrict__ A, int lda, const u16* __restrict__ Bt, int ldb, int K, char* lds_all, Epi epi) {
;     ...
;   const int nk = K >> 6;
;   __syncthreads();
;   G5_LOAD(0);
;   G5_STORE(0);
;   G5_LOAD(64);
;   __syncthreads();
;   for (int kt = 0; kt + 2 < nk; ++kt) {
;     const int cur = kt & 1;
;     G5_COMPUTE(cur);
;     G5_STORE(cur ^ 1);
;     G5_LOAD((kt + 2) << 6);
;     __syncthreads();
;   }
.Lg3_nd3_m0:
	v_subrev_u32_e32 v180, s12, v180
	s_waitcnt lgkmcnt(8)
	v_mfma_f32_32x32x16_bf16 v[114:129], v[194:197], v[166:169], v[114:129]
	ds_read_b128 v[234:237], v179 offset:36960
	s_waitcnt lgkmcnt(7)
	v_mfma_f32_32x32x16_bf16 v[98:113], v[198:201], v[166:169], v[98:113]
	ds_read_b128 v[218:221], v178 offset:96
	s_waitcnt lgkmcnt(7)
	v_mfma_f32_32x32x16_bf16 v[82:97], v[194:197], v[170:173], v[82:97]
	ds_read_b128 v[202:205], v179 offset:41568
	v_mfma_f32_32x32x16_bf16 v[66:81], v[198:201], v[170:173], v[66:81]
	ds_read_b128 v[222:225], v178 offset:4704
	s_waitcnt lgkmcnt(7)
	v_mfma_f32_32x32x16_bf16 v[50:65], v[194:197], v[174:177], v[50:65]
	ds_read_b128 v[226:229], v178 offset:9312
	v_mfma_f32_32x32x16_bf16 v[34:49], v[198:201], v[174:177], v[34:49]
	ds_read_b128 v[230:233], v178 offset:13920
	v_add_u32_e32 v178, s12, v178
	v_add_u32_e32 v179, s12, v179
	s_waitcnt lgkmcnt(8)
	v_mfma_f32_32x32x16_bf16 v[18:33], v[194:197], v[190:193], v[18:33]
	v_mfma_f32_32x32x16_bf16 v[2:17], v[198:201], v[190:193], v[2:17]
	s_sub_u32 s12, 0, s12
	s_add_u32 s98, s98, 0x80
	s_addc_u32 s99, s99, 0
	s_add_u32 s100, s100, 0x80
	s_addc_u32 s101, s101, 0
	s_waitcnt lgkmcnt(0)
	s_barrier
	ds_read_b128 v[194:197], v179 offset:36864
	ds_read_b128 v[166:169], v178
	v_mfma_f32_32x32x16_bf16 v[114:129], v[234:237], v[218:221], v[114:129]
	ds_read_b128 v[198:201], v179 offset:41472
	v_mfma_f32_32x32x16_bf16 v[98:113], v[202:205], v[218:221], v[98:113]
	ds_read_b128 v[170:173], v178 offset:4608
	v_mfma_f32_32x32x16_bf16 v[82:97], v[234:237], v[222:225], v[82:97]
	ds_read_b128 v[174:177], v178 offset:9216
	v_mfma_f32_32x32x16_bf16 v[66:81], v[202:205], v[222:225], v[66:81]
	ds_read_b128 v[190:193], v178 offset:13824
	v_mfma_f32_32x32x16_bf16 v[50:65], v[234:237], v[226:229], v[50:65]
	v_mfma_f32_32x32x16_bf16 v[34:49], v[202:205], v[226:229], v[34:49]
	v_mfma_f32_32x32x16_bf16 v[18:33], v[234:237], v[230:233], v[18:33]
	v_mfma_f32_32x32x16_bf16 v[2:17], v[202:205], v[230:233], v[2:17]
	s_waitcnt lgkmcnt(4)
	v_mfma_f32_32x32x16_bf16 v[114:129], v[194:197], v[166:169], v[114:129]
	ds_read_b128 v[234:237], v179 offset:36896
	s_waitcnt lgkmcnt(4)
	v_mfma_f32_32x32x16_bf16 v[98:113], v[198:201], v[166:169], v[98:113]
	ds_read_b128 v[218:221], v178 offset:32
	s_waitcnt vmcnt(7)
	ds_write_b128 v180, v[130:133]
	global_load_dwordx4 v[130:133], v206, s[98:99]
	s_waitcnt lgkmcnt(5)
	v_mfma_f32_32x32x16_bf16 v[82:97], v[194:197], v[170:173], v[82:97]
	ds_read_b128 v[202:205], v179 offset:41504
	v_mfma_f32_32x32x16_bf16 v[66:81], v[198:201], v[170:173], v[66:81]
	ds_read_b128 v[222:225], v178 offset:4640
	s_waitcnt vmcnt(7)
	ds_write_b128 v180, v[134:137] offset:9216
	global_load_dwordx4 v[134:137], v207, s[98:99]
	s_waitcnt lgkmcnt(7)
	v_mfma_f32_32x32x16_bf16 v[50:65], v[194:197], v[174:177], v[50:65]
	ds_read_b128 v[226:229], v178 offset:9248
	v_mfma_f32_32x32x16_bf16 v[34:49], v[198:201], v[174:177], v[34:49]
	ds_read_b128 v[230:233], v178 offset:13856
	s_waitcnt vmcnt(7)
	ds_write_b128 v180, v[138:141] offset:18432
	global_load_dwordx4 v[138:141], v208, s[98:99]
	s_waitcnt lgkmcnt(9)
	v_mfma_f32_32x32x16_bf16 v[18:33], v[194:197], v[190:193], v[18:33]
	v_mfma_f32_32x32x16_bf16 v[2:17], v[198:201], v[190:193], v[2:17]
	s_waitcnt vmcnt(7)
	ds_write_b128 v180, v[142:145] offset:27648
	global_load_dwordx4 v[142:145], v238, s[98:99]
	s_waitcnt lgkmcnt(8)
	v_mfma_f32_32x32x16_bf16 v[114:129], v[234:237], v[218:221], v[114:129]
	ds_read_b128 v[194:197], v179 offset:36928
	s_waitcnt lgkmcnt(7)
	v_mfma_f32_32x32x16_bf16 v[98:113], v[202:205], v[218:221], v[98:113]
	ds_read_b128 v[166:169], v178 offset:64
	s_waitcnt vmcnt(7)
	ds_write_b128 v180, v[146:149] offset:36864
	global_load_dwordx4 v[146:149], v206, s[100:101]
	s_waitcnt lgkmcnt(8)
	v_mfma_f32_32x32x16_bf16 v[82:97], v[234:237], v[222:225], v[82:97]
	ds_read_b128 v[198:201], v179 offset:41536
	v_mfma_f32_32x32x16_bf16 v[66:81], v[202:205], v[222:225], v[66:81]
	ds_read_b128 v[170:173], v178 offset:4672
	s_waitcnt vmcnt(7)
	ds_write_b128 v180, v[150:153] offset:46080
	global_load_dwordx4 v[150:153], v207, s[100:101]
	s_waitcnt lgkmcnt(9)
	v_mfma_f32_32x32x16_bf16 v[50:65], v[234:237], v[226:229], v[50:65]
	ds_read_b128 v[174:177], v178 offset:9280
	v_mfma_f32_32x32x16_bf16 v[34:49], v[202:205], v[226:229], v[34:49]
	ds_read_b128 v[190:193], v178 offset:13888
	s_waitcnt vmcnt(7)
	ds_write_b128 v180, v[154:157] offset:55296
	global_load_dwordx4 v[154:157], v208, s[100:101]
	s_waitcnt lgkmcnt(11)
	v_mfma_f32_32x32x16_bf16 v[18:33], v[234:237], v[230:233], v[18:33]
	v_mfma_f32_32x32x16_bf16 v[2:17], v[202:205], v[230:233], v[2:17]
	s_waitcnt vmcnt(7)
	ds_write_b128 v180, v[158:161] offset:64512
	global_load_dwordx4 v[158:161], v238, s[100:101]
	s_cmp_eq_u32 s32, 0
	s_cbranch_scc1 .Lg3_nd4_m0
	global_store_dwordx4 v253, v[244:247], s[50:51]
	v_add_u32_e32 v253, 0x16000, v253
.Lg3_nd4_m0:
	v_subrev_u32_e32 v180, s12, v180
	s_waitcnt lgkmcnt(8)
	v_mfma_f32_32x32x16_bf16 v[114:129], v[194:197], v[166:169], v[114:129]
	ds_read_b128 v[234:237], v179 offset:36960
	s_waitcnt lgkmcnt(7)
	v_mfma_f32_32x32x16_bf16 v[98:113], v[198:201], v[166:169], v[98:113]
	ds_read_b128 v[218:221], v178 offset:96
	s_waitcnt lgkmcnt(7)
	v_mfma_f32_32x32x16_bf16 v[82:97], v[194:197], v[170:173], v[82:97]
	ds_read_b128 v[202:205], v179 offset:41568
	v_mfma_f32_32x32x16_bf16 v[66:81], v[198:201], v[170:173], v[66:81]
	ds_read_b128 v[222:225], v178 offset:4704
	s_waitcnt lgkmcnt(7)
	v_mfma_f32_32x32x16_bf16 v[50:65], v[194:197], v[174:177], v[50:65]
	ds_read_b128 v[226:229], v178 offset:9312
	v_mfma_f32_32x32x16_bf16 v[34:49], v[198:201], v[174:177], v[34:49]
	ds_read_b128 v[230:233], v178 offset:13920
	v_add_u32_e32 v178, s12, v178
	v_add_u32_e32 v179, s12, v179
	s_waitcnt lgkmcnt(8)
	v_mfma_f32_32x32x16_bf16 v[18:33], v[194:197], v[190:193], v[18:33]
	v_mfma_f32_32x32x16_bf16 v[2:17], v[198:201], v[190:193], v[2:17]
	s_sub_u32 s12, 0, s12
	s_add_u32 s98, s98, 0x80
	s_addc_u32 s99, s99, 0
	s_add_u32 s100, s100, 0x80
	s_addc_u32 s101, s101, 0
	s_waitcnt lgkmcnt(0)
	s_mov_b32 s32, 0

; DI void gemm_phase(const Params& p, int layer, int mode, int nrows, char* lds_all) {
;     ...
;       if (mode == 0 || mode == 2) {
;         for (int idx = tid; idx < 128 * 32; idx += 512) {
;           const int rr = idx >> 5, c8 = (idx & 31) * 8;
;           const int row = m0 + half * 128 + rr, col = n0 + c8;
;           const float4 v0 = *(const float4*)(Cs + rr * CSW + c8), v1 = *(const float4*)(Cs + rr * CSW + c8 + 4);
;           if (mode == 0) {
;             uint4 o;
;             o.x = pack2(v0.x, v0.y); o.y = pack2(v0.z, v0.w); o.z = pack2(v1.x, v1.y); o.w = pack2(v1.z, v1.w);
;             *(uint4*)((u16*)(p.ws + O_Z) + (size_t)row * ZW + col) = o;
.Lg3_nok2_m0:
	v_lshrrev_b32_e32 v237, 5, v165
	v_and_b32_e32 v194, 31, v165
	v_mul_u32_u24_e32 v235, 0x208, v237
	v_lshl_add_u32 v235, v194, 4, v235
	ds_read2_b64 v[2:5], v235 offset1:1
	v_add_u32_e32 v235, 0x2080, v235
	ds_read2_b64 v[6:9], v235 offset1:1
	v_add_u32_e32 v235, 0x2080, v235
	ds_read2_b64 v[10:13], v235 offset1:1
	v_add_u32_e32 v235, 0x2080, v235
	ds_read2_b64 v[14:17], v235 offset1:1
	v_add_u32_e32 v235, 0x2080, v235
	ds_read2_b64 v[18:21], v235 offset1:1
	v_add_u32_e32 v235, 0x2080, v235
	ds_read2_b64 v[22:25], v235 offset1:1
	v_add_u32_e32 v235, 0x2080, v235
	ds_read2_b64 v[26:29], v235 offset1:1
	v_add_u32_e32 v235, 0x2080, v235
	ds_read2_b64 v[30:33], v235 offset1:1
	v_add_u32_e32 v235, 0x2080, v235
	ds_read2_b64 v[34:37], v235 offset1:1
	v_add_u32_e32 v235, 0x2080, v235
	ds_read2_b64 v[38:41], v235 offset1:1
	v_add_u32_e32 v235, 0x2080, v235
	ds_read2_b64 v[42:45], v235 offset1:1
	v_add_u32_e32 v235, 0x2080, v235
	ds_read2_b64 v[182:185], v235 offset1:1
	v_add_u32_e32 v235, 0x2080, v235
	ds_read2_b64 v[186:189], v235 offset1:1
	v_add_u32_e32 v235, 0x2080, v235
	ds_read2_b64 v[210:213], v235 offset1:1
	v_add_u32_e32 v235, 0x2080, v235
	ds_read2_b64 v[240:243], v235 offset1:1
	v_add_u32_e32 v235, 0x2080, v235
	ds_read2_b64 v[244:247], v235 offset1:1
	s_waitcnt lgkmcnt(15)
	global_store_dwordx4 v234, v[2:5], s[50:51]
	v_add_u32_e32 v234, 0x16000, v234
	s_waitcnt lgkmcnt(14)
	global_store_dwordx4 v234, v[6:9], s[50:51]
	v_add_u32_e32 v234, 0x16000, v234
	s_waitcnt lgkmcnt(13)
	global_store_dwordx4 v234, v[10:13], s[50:51]
	v_add_u32_e32 v234, 0x16000, v234
	s_waitcnt lgkmcnt(12)
	global_store_dwordx4 v234, v[14:17], s[50:51]
	v_add_u32_e32 v234, 0x16000, v234
	s_waitcnt lgkmcnt(11)
	global_store_dwordx4 v234, v[18:21], s[50:51]
	v_add_u32_e32 v234, 0x16000, v234
	s_waitcnt lgkmcnt(10)
	global_store_dwordx4 v234, v[22:25], s[50:51]
	v_add_u32_e32 v234, 0x16000, v234
	s_waitcnt lgkmcnt(9)
	global_store_dwordx4 v234, v[26:29], s[50:51]
	v_add_u32_e32 v234, 0x16000, v234
	s_waitcnt lgkmcnt(8)
	global_store_dwordx4 v234, v[30:33], s[50:51]
	v_add_u32_e32 v234, 0x16000, v234
	s_waitcnt lgkmcnt(7)
	global_store_dwordx4 v234, v[34:37], s[50:51]
	v_add_u32_e32 v234, 0x16000, v234
	s_waitcnt lgkmcnt(6)
	global_store_dwordx4 v234, v[38:41], s[50:51]
	v_add_u32_e32 v234, 0x16000, v234
	s_waitcnt lgkmcnt(5)
	global_store_dwordx4 v234, v[42:45], s[50:51]
	v_add_u32_e32 v234, 0x16000, v234
	s_waitcnt lgkmcnt(0)
	v_mov_b32_e32 v253, v234
	s_mov_b32 s32, 1
	s_cmp_lg_u32 s10, 0
	s_cbranch_scc1 .Lg3_defer_m0
	global_store_dwordx4 v253, v[182:185], s[50:51]
	v_add_u32_e32 v253, 0x16000, v253
	global_store_dwordx4 v253, v[186:189], s[50:51]
	v_add_u32_e32 v253, 0x16000, v253
	global_store_dwordx4 v253, v[210:213], s[50:51]
	v_add_u32_e32 v253, 0x16000, v253
	global_store_dwordx4 v253, v[240:243], s[50:51]
	v_add_u32_e32 v253, 0x16000, v253
	global_store_dwordx4 v253, v[244:247], s[50:51]
	s_mov_b32 s32, 0
.Lg3_defer_m0:
	s_cmp_lg_u32 s10, 0
	s_cbranch_scc1 .Lg3_start_m0
	v_mov_b32_e32 v190, 0x10c20
	v_mov_b32_e32 v191, 0x11040
	v_mov_b32_e32 v192, 0x11460
	v_mov_b32_e32 v193, 0x12900
	v_mov_b32_e32 v194, 0x12d20
	v_mov_b32_e32 v195, 0x13140
	v_mov_b32_e32 v196, 0x13560
	v_mov_b32_e32 v197, 0x14a00
	v_mov_b32_e32 v198, 0x14e20
	v_mov_b32_e32 v199, 0x15240
	v_mov_b32_e32 v200, 0x15660
	v_mov_b32_e32 v201, 0x16b00
	v_mov_b32_e32 v202, 0x16f20
	v_mov_b32_e32 v203, 0x17340
	v_mov_b32_e32 v204, 0x17760
	v_mov_b32_e32 v205, 0x18c00
	v_mov_b32_e32 v206, 0x19020
	v_mov_b32_e32 v207, 0x19440
	v_mov_b32_e32 v208, 0x10800
	v_mov_b32_e32 v210, 0xff
	v_mov_b32_e32 v211, 0xfff
	v_bfrev_b32_e32 v212, 4.0
	v_mov_b32_e32 v213, 0x1002
	v_mov_b32_e32 v240, 0x19860
	v_mov_b32_e32 v241, 0x1ad00
	v_mov_b32_e32 v242, 0x1b120
	v_mov_b32_e32 v243, 0x1b540
	v_mov_b32_e32 v244, 0x1b960
	v_mov_b32_e32 v245, 0x1ce00
	v_mov_b32_e32 v246, 0x1d220
	v_mov_b32_e32 v247, 0x1d640
	s_branch .LBB0_209

; DI void gemm_phase(const Params& p, int layer, int mode, int nrows, char* lds_all) {
;     ...
;   for (int i = jb;; i += nj) {
;     const int srl = i / per, rem = i - srl * per;
;     const int sr = xcd + nx * srl;
;     if (sr >= nsr) break;
;     const int tn = rem >> 1, tm = sr * 2 + (rem & 1);
;     const int m0 = tm * 256, n0 = tn * 256;
.LBB0_833:
	s_mov_b32 s32, 0
	s_lshl_b32 s24, s4, 5
	s_sub_i32 s24, s21, s24
	s_xor_b32 s11, s4, 1
	s_lshl_b32 s11, s11, 3
	s_add_i32 s11, s11, s19
	s_cmp_lt_i32 s11, s36
	s_cbranch_scc0 .Lm2map_old_a
	s_and_b32 s11, s4, 0xfffffffe
	s_bfe_u32 s5, s24, 0x10001
	s_add_i32 s11, s11, s5
	s_lshl_b32 s11, s11, 3
	s_add_i32 s11, s11, s19
	s_lshl_b32 s11, s11, 9
	s_and_b32 s5, s24, 1
	s_lshl_b32 s5, s5, 8
	s_or_b32 s22, s11, s5
	s_lshr_b32 s23, s24, 2
	s_and_b32 s5, s4, 1
	s_lshl_b32 s5, s5, 3
	s_add_i32 s23, s23, s5
	s_lshl_b32 s23, s23, 8
	s_branch .Lm2map_done_a

; #define G5_LOAD(k0)                                                                 \
;   {                                                                                 \
;     _Pragma("unroll") for (int i_ = 0; i_ < 4; ++i_) ra[i_] = ldg16(Ap + (size_t)(i_ * 64) * lda + (k0)); \
;     _Pragma("unroll") for (int i_ = 0; i_ < 4; ++i_) rb[i_] = ldg16(Bp + (size_t)(i_ * 64) * ldb + (k0)); \
;   }
; #define G5_STORE(s)                                                                 \
;   {                                                                                 \
;     _Pragma("unroll") for (int i_ = 0; i_ < 4; ++i_) *(u32x4*)(Sw + (s) * STG + i_ * 64 * GS) = ra[i_]; \
;     _Pragma("unroll") for (int i_ = 0; i_ < 4; ++i_) *(u32x4*)(Sw + (s) * STG + 256 * GS + i_ * 64 * GS) = rb[i_]; \
;   }
; template <typename Epi>
; DI void gemm_tile512(const u16* __restrict__ A, int lda, const u16* __restrict__ Bt, int ldb, int K, char* lds_all, Epi epi) {
;     ...
;   const int nk = K >> 6;
;   __syncthreads();
;   G5_LOAD(0);
;   G5_STORE(0);
;   G5_LOAD(64);
;   __syncthreads();
;   for (int kt = 0; kt + 2 < nk; ++kt) {
;     const int cur = kt & 1;
;     G5_COMPUTE(cur);
;     G5_STORE(cur ^ 1);
;     G5_LOAD((kt + 2) << 6);
;     __syncthreads();
;   }
; DI void gemm_phase(const Params& p, int layer, int mode, int nrows, char* lds_all) {
;     ...
;   for (int i = jb;; i += nj) {
;     const int srl = i / per, rem = i - srl * per;
;     const int sr = xcd + nx * srl;
;     if (sr >= nsr) break;
;     const int tn = rem >> 1, tm = sr * 2 + (rem & 1);
;     const int m0 = tm * 256, n0 = tn * 256;
;     gemm_tile512(A + (size_t)m0 * lda, lda, Bt + (size_t)n0 * ldb, ldb, K, lds_all, [&](int half) {
.Lm2map_done_a:
	s_mul_i32 s4, s22, 0x900
	v_readlane_b32 s8, v250, 46
	s_mul_hi_i32 s5, s22, 0x900
	s_add_u32 s4, s8, s4
	v_readlane_b32 s8, v250, 47
	s_addc_u32 s5, s8, s5
	s_mul_i32 s8, s23, 0x900
	s_mul_hi_i32 s9, s23, 0x900
	s_add_u32 s8, s14, s8
	s_addc_u32 s9, s15, s9
	s_mov_b64 s[26:27], s[4:5]
	s_mov_b64 s[98:99], s[26:27]
	s_mov_b64 s[100:101], s[8:9]
	v_lshrrev_b32_e32 v239, 3, v165
	v_and_b32_e32 v0, 7, v165
	v_mul_u32_u24_e32 v206, 0x900, v239
	v_lshl_add_u32 v206, v0, 4, v206
	v_add_u32_e32 v207, 0x24000, v206
	v_add_u32_e32 v208, 0x48000, v206
	v_add_u32_e32 v238, 0x6c000, v206
	global_load_dwordx4 v[130:133], v206, s[98:99]
	global_load_dwordx4 v[134:137], v207, s[98:99]
	global_load_dwordx4 v[138:141], v208, s[98:99]
	global_load_dwordx4 v[142:145], v238, s[98:99]
	global_load_dwordx4 v[146:149], v206, s[100:101]
	global_load_dwordx4 v[150:153], v207, s[100:101]
	global_load_dwordx4 v[154:157], v208, s[100:101]
	global_load_dwordx4 v[158:161], v238, s[100:101]
	global_load_dwordx4 v[218:221], v206, s[98:99] offset:128
	global_load_dwordx4 v[222:225], v207, s[98:99] offset:128
	global_load_dwordx4 v[226:229], v208, s[98:99] offset:128
	global_load_dwordx4 v[230:233], v238, s[98:99] offset:128
	global_load_dwordx4 v[166:169], v206, s[100:101] offset:128
	global_load_dwordx4 v[170:173], v207, s[100:101] offset:128
	global_load_dwordx4 v[174:177], v208, s[100:101] offset:128
	global_load_dwordx4 v[190:193], v238, s[100:101] offset:128
	s_add_u32 s98, s98, 0x100
	s_addc_u32 s99, s99, 0
	s_add_u32 s100, s100, 0x100
	s_addc_u32 s101, s101, 0
	global_load_dwordx4 v[66:69], v206, s[98:99]
	global_load_dwordx4 v[70:73], v207, s[98:99]
	global_load_dwordx4 v[74:77], v208, s[98:99]
	global_load_dwordx4 v[78:81], v238, s[98:99]
	global_load_dwordx4 v[82:85], v206, s[100:101]
	global_load_dwordx4 v[86:89], v207, s[100:101]
	global_load_dwordx4 v[90:93], v208, s[100:101]
	global_load_dwordx4 v[94:97], v238, s[100:101]
	v_lshrrev_b32_e32 v239, 3, v165
	v_and_b32_e32 v0, 7, v165
	v_mul_u32_u24_e32 v180, 0x90, v239
	v_lshl_add_u32 v180, v0, 4, v180
	v_and_b32_e32 v239, 31, v165
	v_bfe_u32 v0, v165, 5, 1
	v_lshrrev_b32_e32 v179, 8, v165
	v_lshl_or_b32 v178, v179, 7, v239
	v_mul_u32_u24_e32 v178, 0x90, v178
	v_lshl_add_u32 v178, v0, 4, v178
	v_bfe_u32 v179, v165, 6, 2
	v_lshl_or_b32 v179, v179, 6, v239
	v_mul_u32_u24_e32 v179, 0x90, v179
	v_lshl_add_u32 v179, v0, 4, v179
	s_mov_b32 s11, 0x12000
	s_mov_b32 s12, 9
	s_barrier
	s_waitcnt vmcnt(23)
	ds_write_b128 v180, v[130:133]
	s_waitcnt vmcnt(22)
	ds_write_b128 v180, v[134:137] offset:9216
	s_waitcnt vmcnt(21)
	ds_write_b128 v180, v[138:141] offset:18432
	s_waitcnt vmcnt(20)
	ds_write_b128 v180, v[142:145] offset:27648
	s_waitcnt vmcnt(19)
	ds_write_b128 v180, v[146:149] offset:36864
	s_waitcnt vmcnt(18)
	ds_write_b128 v180, v[150:153] offset:46080
	s_waitcnt vmcnt(17)
	ds_write_b128 v180, v[154:157] offset:55296
	s_waitcnt vmcnt(16)
	ds_write_b128 v180, v[158:161] offset:64512
	v_add_u32_e32 v180, 0x12000, v180
	s_waitcnt vmcnt(15)
	ds_write_b128 v180, v[218:221]
	s_waitcnt vmcnt(14)
	ds_write_b128 v180, v[222:225] offset:9216
	s_waitcnt vmcnt(13)
	ds_write_b128 v180, v[226:229] offset:18432
	s_waitcnt vmcnt(12)
	ds_write_b128 v180, v[230:233] offset:27648
	s_waitcnt vmcnt(11)
	ds_write_b128 v180, v[166:169] offset:36864
	s_waitcnt vmcnt(10)
	ds_write_b128 v180, v[170:173] offset:46080
	s_waitcnt vmcnt(9)
	ds_write_b128 v180, v[174:177] offset:55296
	s_waitcnt vmcnt(8)
	ds_write_b128 v180, v[190:193] offset:64512
	s_waitcnt vmcnt(0)
	v_mov_b64_e32 v[130:131], v[66:67]
	v_mov_b64_e32 v[132:133], v[68:69]
	v_mov_b64_e32 v[134:135], v[70:71]
	v_mov_b64_e32 v[136:137], v[72:73]
	v_mov_b64_e32 v[138:139], v[74:75]
	v_mov_b64_e32 v[140:141], v[76:77]
	v_mov_b64_e32 v[142:143], v[78:79]
	v_mov_b64_e32 v[144:145], v[80:81]
	v_mov_b64_e32 v[146:147], v[82:83]
	v_mov_b64_e32 v[148:149], v[84:85]
	v_mov_b64_e32 v[150:151], v[86:87]
	v_mov_b64_e32 v[152:153], v[88:89]
	v_mov_b64_e32 v[154:155], v[90:91]
	v_mov_b64_e32 v[156:157], v[92:93]
	v_mov_b64_e32 v[158:159], v[94:95]
	v_mov_b64_e32 v[160:161], v[96:97]
	s_waitcnt lgkmcnt(0)
	s_branch .Lg3_k_m2
.Lg3_start_m2:
	v_lshrrev_b32_e32 v239, 3, v165
	v_and_b32_e32 v0, 7, v165
	v_mul_u32_u24_e32 v180, 0x90, v239
	v_lshl_add_u32 v180, v0, 4, v180
	v_and_b32_e32 v239, 31, v165
	v_bfe_u32 v0, v165, 5, 1
	v_lshrrev_b32_e32 v179, 8, v165
	v_lshl_or_b32 v178, v179, 7, v239
	v_mul_u32_u24_e32 v178, 0x90, v178
	v_lshl_add_u32 v178, v0, 4, v178
	v_bfe_u32 v179, v165, 6, 2
	v_lshl_or_b32 v179, v179, 6, v239
	v_mul_u32_u24_e32 v179, 0x90, v179
	v_lshl_add_u32 v179, v0, 4, v179
	s_mov_b32 s11, 0x12000
	s_mov_b32 s12, 9
	s_barrier
	s_waitcnt vmcnt(34)
	ds_write_b128 v180, v[130:133]
	s_waitcnt vmcnt(33)
	ds_write_b128 v180, v[134:137] offset:9216
	s_waitcnt vmcnt(32)
	ds_write_b128 v180, v[138:141] offset:18432
	s_waitcnt vmcnt(31)
	ds_write_b128 v180, v[142:145] offset:27648
	s_waitcnt vmcnt(30)
	ds_write_b128 v180, v[146:149] offset:36864
	s_waitcnt vmcnt(29)
	ds_write_b128 v180, v[150:153] offset:46080
	s_waitcnt vmcnt(28)
	ds_write_b128 v180, v[154:157] offset:55296
	s_waitcnt vmcnt(27)
	ds_write_b128 v180, v[158:161] offset:64512
	v_add_u32_e32 v180, 0x12000, v180
	s_waitcnt vmcnt(26)
	ds_write_b128 v180, v[218:221]
	s_waitcnt vmcnt(25)
	ds_write_b128 v180, v[222:225] offset:9216
	s_waitcnt vmcnt(24)
	ds_write_b128 v180, v[226:229] offset:18432
	s_waitcnt vmcnt(23)
	ds_write_b128 v180, v[230:233] offset:27648
	s_waitcnt vmcnt(22)
	ds_write_b128 v180, v[166:169] offset:36864
	s_waitcnt vmcnt(21)
	ds_write_b128 v180, v[170:173] offset:46080
	s_waitcnt vmcnt(20)
	ds_write_b128 v180, v[174:177] offset:55296
	s_waitcnt vmcnt(19)
	ds_write_b128 v180, v[190:193] offset:64512
	s_waitcnt vmcnt(11)
	v_mov_b64_e32 v[130:131], v[66:67]
	v_mov_b64_e32 v[132:133], v[68:69]
	v_mov_b64_e32 v[134:135], v[70:71]
	v_mov_b64_e32 v[136:137], v[72:73]
	v_mov_b64_e32 v[138:139], v[74:75]
	v_mov_b64_e32 v[140:141], v[76:77]
	v_mov_b64_e32 v[142:143], v[78:79]
	v_mov_b64_e32 v[144:145], v[80:81]
	v_mov_b64_e32 v[146:147], v[82:83]
	v_mov_b64_e32 v[148:149], v[84:85]
	v_mov_b64_e32 v[150:151], v[86:87]
	v_mov_b64_e32 v[152:153], v[88:89]
	v_mov_b64_e32 v[154:155], v[90:91]
	v_mov_b64_e32 v[156:157], v[92:93]
	v_mov_b64_e32 v[158:159], v[94:95]
	v_mov_b64_e32 v[160:161], v[96:97]
	s_waitcnt lgkmcnt(0)
; #define G5_LOAD(k0)                                                                 \
;   {                                                                                 \
;     _Pragma("unroll") for (int i_ = 0; i_ < 4; ++i_) ra[i_] = ldg16(Ap + (size_t)(i_ * 64) * lda + (k0)); \
;     _Pragma("unroll") for (int i_ = 0; i_ < 4; ++i_) rb[i_] = ldg16(Bp + (size_t)(i_ * 64) * ldb + (k0)); \
;   }
; #define G5_STORE(s)                                                                 \
;   {                                                                                 \
;     _Pragma("unroll") for (int i_ = 0; i_ < 4; ++i_) *(u32x4*)(Sw + (s) * STG + i_ * 64 * GS) = ra[i_]; \
;     _Pragma("unroll") for (int i_ = 0; i_ < 4; ++i_) *(u32x4*)(Sw + (s) * STG + 256 * GS + i_ * 64 * GS) = rb[i_]; \
;   }
; template <typename Epi>
; DI void gemm_tile512(const u16* __restrict__ A, int lda, const u16* __restrict__ Bt, int ldb, int K, char* lds_all, Epi epi) {
;     ...
;   const int nk = K >> 6;
;   __syncthreads();
;   G5_LOAD(0);
;   G5_STORE(0);
;   G5_LOAD(64);
;   __syncthreads();
;   for (int kt = 0; kt + 2 < nk; ++kt) {
;     const int cur = kt & 1;
;     G5_COMPUTE(cur);
;     G5_STORE(cur ^ 1);
;     G5_LOAD((kt + 2) << 6);
;     __syncthreads();
;   }
.Lg3_k_m2:
	s_barrier
	ds_read_b128 v[194:197], v179 offset:36864
	ds_read_b128 v[166:169], v178
	ds_read_b128 v[198:201], v179 offset:41472
	ds_read_b128 v[170:173], v178 offset:4608
	ds_read_b128 v[174:177], v178 offset:9216
	ds_read_b128 v[190:193], v178 offset:13824
	s_waitcnt lgkmcnt(4)
	v_mfma_f32_32x32x16_bf16 v[114:129], v[194:197], v[166:169], 0
	ds_read_b128 v[234:237], v179 offset:36896
	s_waitcnt lgkmcnt(4)
	v_mfma_f32_32x32x16_bf16 v[98:113], v[198:201], v[166:169], 0
	ds_read_b128 v[218:221], v178 offset:32
	s_waitcnt lgkmcnt(4)
	v_mfma_f32_32x32x16_bf16 v[82:97], v[194:197], v[170:173], 0
	ds_read_b128 v[202:205], v179 offset:41504
	v_mfma_f32_32x32x16_bf16 v[66:81], v[198:201], v[170:173], 0
	ds_read_b128 v[222:225], v178 offset:4640
	s_waitcnt lgkmcnt(5)
	v_mfma_f32_32x32x16_bf16 v[50:65], v[194:197], v[174:177], 0
	ds_read_b128 v[226:229], v178 offset:9248
	v_mfma_f32_32x32x16_bf16 v[34:49], v[198:201], v[174:177], 0
	ds_read_b128 v[230:233], v178 offset:13856
	s_waitcnt lgkmcnt(6)
	v_mfma_f32_32x32x16_bf16 v[18:33], v[194:197], v[190:193], 0
	v_mfma_f32_32x32x16_bf16 v[2:17], v[198:201], v[190:193], 0
	s_waitcnt lgkmcnt(4)
	v_mfma_f32_32x32x16_bf16 v[114:129], v[234:237], v[218:221], v[114:129]
	ds_read_b128 v[194:197], v179 offset:36928
	s_waitcnt lgkmcnt(4)
	v_mfma_f32_32x32x16_bf16 v[98:113], v[202:205], v[218:221], v[98:113]
	ds_read_b128 v[166:169], v178 offset:64
	s_waitcnt lgkmcnt(4)
	v_mfma_f32_32x32x16_bf16 v[82:97], v[234:237], v[222:225], v[82:97]
	ds_read_b128 v[198:201], v179 offset:41536
	v_mfma_f32_32x32x16_bf16 v[66:81], v[202:205], v[222:225], v[66:81]
	ds_read_b128 v[170:173], v178 offset:4672
	s_waitcnt lgkmcnt(5)
	v_mfma_f32_32x32x16_bf16 v[50:65], v[234:237], v[226:229], v[50:65]
	ds_read_b128 v[174:177], v178 offset:9280
	v_mfma_f32_32x32x16_bf16 v[34:49], v[202:205], v[226:229], v[34:49]
	ds_read_b128 v[190:193], v178 offset:13888
	s_waitcnt lgkmcnt(6)
	v_mfma_f32_32x32x16_bf16 v[18:33], v[234:237], v[230:233], v[18:33]
	v_mfma_f32_32x32x16_bf16 v[2:17], v[202:205], v[230:233], v[2:17]
	s_cmp_eq_u32 s32, 0
	s_cbranch_scc1 .Lg3_nd0_m2
	global_store_dwordx4 v253, v[182:185], s[50:51]
	v_add_u32_e32 v253, 0x21000, v253
.Lg3_nd0_m2:
	v_subrev_u32_e32 v180, s11, v180
	s_waitcnt lgkmcnt(4)
	v_mfma_f32_32x32x16_bf16 v[114:129], v[194:197], v[166:169], v[114:129]
	ds_read_b128 v[234:237], v179 offset:36960
	s_waitcnt lgkmcnt(4)
	v_mfma_f32_32x32x16_bf16 v[98:113], v[198:201], v[166:169], v[98:113]
	ds_read_b128 v[218:221], v178 offset:96
	s_waitcnt lgkmcnt(4)
	v_mfma_f32_32x32x16_bf16 v[82:97], v[194:197], v[170:173], v[82:97]
	ds_read_b128 v[202:205], v179 offset:41568
	v_mfma_f32_32x32x16_bf16 v[66:81], v[198:201], v[170:173], v[66:81]
	ds_read_b128 v[222:225], v178 offset:4704
	s_waitcnt lgkmcnt(5)
	v_mfma_f32_32x32x16_bf16 v[50:65], v[194:197], v[174:177], v[50:65]
	ds_read_b128 v[226:229], v178 offset:9312
	v_mfma_f32_32x32x16_bf16 v[34:49], v[198:201], v[174:177], v[34:49]
	ds_read_b128 v[230:233], v178 offset:13920
	v_add_u32_e32 v178, s11, v178
	v_add_u32_e32 v179, s11, v179
	s_waitcnt lgkmcnt(6)
	v_mfma_f32_32x32x16_bf16 v[18:33], v[194:197], v[190:193], v[18:33]
	v_mfma_f32_32x32x16_bf16 v[2:17], v[198:201], v[190:193], v[2:17]
	s_sub_u32 s11, 0, s11
	s_add_u32 s98, s98, 0x80
	s_addc_u32 s99, s99, 0
	s_add_u32 s100, s100, 0x80
	s_addc_u32 s101, s101, 0
	s_waitcnt lgkmcnt(0)
	s_barrier
	ds_read_b128 v[194:197], v179 offset:36864
	ds_read_b128 v[166:169], v178
	v_mfma_f32_32x32x16_bf16 v[114:129], v[234:237], v[218:221], v[114:129]
	ds_read_b128 v[198:201], v179 offset:41472
	v_mfma_f32_32x32x16_bf16 v[98:113], v[202:205], v[218:221], v[98:113]
	ds_read_b128 v[170:173], v178 offset:4608
	v_mfma_f32_32x32x16_bf16 v[82:97], v[234:237], v[222:225], v[82:97]
	ds_read_b128 v[174:177], v178 offset:9216
	v_mfma_f32_32x32x16_bf16 v[66:81], v[202:205], v[222:225], v[66:81]
	ds_read_b128 v[190:193], v178 offset:13824
	v_mfma_f32_32x32x16_bf16 v[50:65], v[234:237], v[226:229], v[50:65]
	v_mfma_f32_32x32x16_bf16 v[34:49], v[202:205], v[226:229], v[34:49]
	v_mfma_f32_32x32x16_bf16 v[18:33], v[234:237], v[230:233], v[18:33]
	v_mfma_f32_32x32x16_bf16 v[2:17], v[202:205], v[230:233], v[2:17]
	s_waitcnt lgkmcnt(4)
	v_mfma_f32_32x32x16_bf16 v[114:129], v[194:197], v[166:169], v[114:129]
	ds_read_b128 v[234:237], v179 offset:36896
	s_waitcnt lgkmcnt(4)
	v_mfma_f32_32x32x16_bf16 v[98:113], v[198:201], v[166:169], v[98:113]
	ds_read_b128 v[218:221], v178 offset:32
	ds_write_b128 v180, v[130:133]
	global_load_dwordx4 v[130:133], v206, s[98:99]
	s_waitcnt lgkmcnt(5)
	v_mfma_f32_32x32x16_bf16 v[82:97], v[194:197], v[170:173], v[82:97]
	ds_read_b128 v[202:205], v179 offset:41504
	v_mfma_f32_32x32x16_bf16 v[66:81], v[198:201], v[170:173], v[66:81]
	ds_read_b128 v[222:225], v178 offset:4640
	ds_write_b128 v180, v[134:137] offset:9216
	global_load_dwordx4 v[134:137], v207, s[98:99]
	s_waitcnt lgkmcnt(7)
	v_mfma_f32_32x32x16_bf16 v[50:65], v[194:197], v[174:177], v[50:65]
	ds_read_b128 v[226:229], v178 offset:9248
	v_mfma_f32_32x32x16_bf16 v[34:49], v[198:201], v[174:177], v[34:49]
	ds_read_b128 v[230:233], v178 offset:13856
	ds_write_b128 v180, v[138:141] offset:18432
	global_load_dwordx4 v[138:141], v208, s[98:99]
	s_waitcnt lgkmcnt(9)
	v_mfma_f32_32x32x16_bf16 v[18:33], v[194:197], v[190:193], v[18:33]
	v_mfma_f32_32x32x16_bf16 v[2:17], v[198:201], v[190:193], v[2:17]
	ds_write_b128 v180, v[142:145] offset:27648
	global_load_dwordx4 v[142:145], v238, s[98:99]
	s_waitcnt lgkmcnt(8)
	v_mfma_f32_32x32x16_bf16 v[114:129], v[234:237], v[218:221], v[114:129]
	ds_read_b128 v[194:197], v179 offset:36928
	s_waitcnt lgkmcnt(7)
	v_mfma_f32_32x32x16_bf16 v[98:113], v[202:205], v[218:221], v[98:113]
	ds_read_b128 v[166:169], v178 offset:64
	ds_write_b128 v180, v[146:149] offset:36864
	global_load_dwordx4 v[146:149], v206, s[100:101]
	s_waitcnt lgkmcnt(8)
	v_mfma_f32_32x32x16_bf16 v[82:97], v[234:237], v[222:225], v[82:97]
	ds_read_b128 v[198:201], v179 offset:41536
	v_mfma_f32_32x32x16_bf16 v[66:81], v[202:205], v[222:225], v[66:81]
	ds_read_b128 v[170:173], v178 offset:4672
	ds_write_b128 v180, v[150:153] offset:46080
	global_load_dwordx4 v[150:153], v207, s[100:101]
	s_waitcnt lgkmcnt(9)
	v_mfma_f32_32x32x16_bf16 v[50:65], v[234:237], v[226:229], v[50:65]
	ds_read_b128 v[174:177], v178 offset:9280
	v_mfma_f32_32x32x16_bf16 v[34:49], v[202:205], v[226:229], v[34:49]
	ds_read_b128 v[190:193], v178 offset:13888
	ds_write_b128 v180, v[154:157] offset:55296
	global_load_dwordx4 v[154:157], v208, s[100:101]
	s_waitcnt lgkmcnt(11)
	v_mfma_f32_32x32x16_bf16 v[18:33], v[234:237], v[230:233], v[18:33]
	v_mfma_f32_32x32x16_bf16 v[2:17], v[202:205], v[230:233], v[2:17]
	ds_write_b128 v180, v[158:161] offset:64512
	global_load_dwordx4 v[158:161], v238, s[100:101]
	s_cmp_eq_u32 s32, 0
	s_cbranch_scc1 .Lg3_nd1_m2
	global_store_dwordx4 v253, v[186:189], s[50:51]
	v_add_u32_e32 v253, 0x21000, v253
; #define G5_LOAD(k0)                                                                 \
;   {                                                                                 \
;     _Pragma("unroll") for (int i_ = 0; i_ < 4; ++i_) ra[i_] = ldg16(Ap + (size_t)(i_ * 64) * lda + (k0)); \
;     _Pragma("unroll") for (int i_ = 0; i_ < 4; ++i_) rb[i_] = ldg16(Bp + (size_t)(i_ * 64) * ldb + (k0)); \
;   }
; #define G5_STORE(s)                                                                 \
;   {                                                                                 \
;     _Pragma("unroll") for (int i_ = 0; i_ < 4; ++i_) *(u32x4*)(Sw + (s) * STG + i_ * 64 * GS) = ra[i_]; \
;     _Pragma("unroll") for (int i_ = 0; i_ < 4; ++i_) *(u32x4*)(Sw + (s) * STG + 256 * GS + i_ * 64 * GS) = rb[i_]; \
;   }
; template <typename Epi>
; DI void gemm_tile512(const u16* __restrict__ A, int lda, const u16* __restrict__ Bt, int ldb, int K, char* lds_all, Epi epi) {
;     ...
;   const int nk = K >> 6;
;   __syncthreads();
;   G5_LOAD(0);
;   G5_STORE(0);
;   G5_LOAD(64);
;   __syncthreads();
;   for (int kt = 0; kt + 2 < nk; ++kt) {
;     const int cur = kt & 1;
;     G5_COMPUTE(cur);
;     G5_STORE(cur ^ 1);
;     G5_LOAD((kt + 2) << 6);
;     __syncthreads();
;   }
.Lg3_nd1_m2:
	v_subrev_u32_e32 v180, s11, v180
	s_waitcnt lgkmcnt(8)
	v_mfma_f32_32x32x16_bf16 v[114:129], v[194:197], v[166:169], v[114:129]
	ds_read_b128 v[234:237], v179 offset:36960
	s_waitcnt lgkmcnt(7)
	v_mfma_f32_32x32x16_bf16 v[98:113], v[198:201], v[166:169], v[98:113]
	ds_read_b128 v[218:221], v178 offset:96
	s_waitcnt lgkmcnt(7)
	v_mfma_f32_32x32x16_bf16 v[82:97], v[194:197], v[170:173], v[82:97]
	ds_read_b128 v[202:205], v179 offset:41568
	v_mfma_f32_32x32x16_bf16 v[66:81], v[198:201], v[170:173], v[66:81]
	ds_read_b128 v[222:225], v178 offset:4704
	s_waitcnt lgkmcnt(7)
	v_mfma_f32_32x32x16_bf16 v[50:65], v[194:197], v[174:177], v[50:65]
	ds_read_b128 v[226:229], v178 offset:9312
	v_mfma_f32_32x32x16_bf16 v[34:49], v[198:201], v[174:177], v[34:49]
	ds_read_b128 v[230:233], v178 offset:13920
	v_add_u32_e32 v178, s11, v178
	v_add_u32_e32 v179, s11, v179
	s_waitcnt lgkmcnt(8)
	v_mfma_f32_32x32x16_bf16 v[18:33], v[194:197], v[190:193], v[18:33]
	v_mfma_f32_32x32x16_bf16 v[2:17], v[198:201], v[190:193], v[2:17]
	s_sub_u32 s11, 0, s11
	s_add_u32 s98, s98, 0x80
	s_addc_u32 s99, s99, 0
	s_add_u32 s100, s100, 0x80
	s_addc_u32 s101, s101, 0
	s_waitcnt lgkmcnt(0)
	s_barrier
	ds_read_b128 v[194:197], v179 offset:36864
	ds_read_b128 v[166:169], v178
	v_mfma_f32_32x32x16_bf16 v[114:129], v[234:237], v[218:221], v[114:129]
	ds_read_b128 v[198:201], v179 offset:41472
	v_mfma_f32_32x32x16_bf16 v[98:113], v[202:205], v[218:221], v[98:113]
	ds_read_b128 v[170:173], v178 offset:4608
	v_mfma_f32_32x32x16_bf16 v[82:97], v[234:237], v[222:225], v[82:97]
	ds_read_b128 v[174:177], v178 offset:9216
	v_mfma_f32_32x32x16_bf16 v[66:81], v[202:205], v[222:225], v[66:81]
	ds_read_b128 v[190:193], v178 offset:13824
	v_mfma_f32_32x32x16_bf16 v[50:65], v[234:237], v[226:229], v[50:65]
	v_mfma_f32_32x32x16_bf16 v[34:49], v[202:205], v[226:229], v[34:49]
	v_mfma_f32_32x32x16_bf16 v[18:33], v[234:237], v[230:233], v[18:33]
	v_mfma_f32_32x32x16_bf16 v[2:17], v[202:205], v[230:233], v[2:17]
	s_waitcnt lgkmcnt(4)
	v_mfma_f32_32x32x16_bf16 v[114:129], v[194:197], v[166:169], v[114:129]
	ds_read_b128 v[234:237], v179 offset:36896
	s_waitcnt lgkmcnt(4)
	v_mfma_f32_32x32x16_bf16 v[98:113], v[198:201], v[166:169], v[98:113]
	ds_read_b128 v[218:221], v178 offset:32
	s_waitcnt vmcnt(7)
	ds_write_b128 v180, v[130:133]
	global_load_dwordx4 v[130:133], v206, s[98:99]
	s_waitcnt lgkmcnt(5)
	v_mfma_f32_32x32x16_bf16 v[82:97], v[194:197], v[170:173], v[82:97]
	ds_read_b128 v[202:205], v179 offset:41504
	v_mfma_f32_32x32x16_bf16 v[66:81], v[198:201], v[170:173], v[66:81]
	ds_read_b128 v[222:225], v178 offset:4640
	s_waitcnt vmcnt(7)
	ds_write_b128 v180, v[134:137] offset:9216
	global_load_dwordx4 v[134:137], v207, s[98:99]
	s_waitcnt lgkmcnt(7)
	v_mfma_f32_32x32x16_bf16 v[50:65], v[194:197], v[174:177], v[50:65]
	ds_read_b128 v[226:229], v178 offset:9248
	v_mfma_f32_32x32x16_bf16 v[34:49], v[198:201], v[174:177], v[34:49]
	ds_read_b128 v[230:233], v178 offset:13856
	s_waitcnt vmcnt(7)
	ds_write_b128 v180, v[138:141] offset:18432
	global_load_dwordx4 v[138:141], v208, s[98:99]
	s_waitcnt lgkmcnt(9)
	v_mfma_f32_32x32x16_bf16 v[18:33], v[194:197], v[190:193], v[18:33]
	v_mfma_f32_32x32x16_bf16 v[2:17], v[198:201], v[190:193], v[2:17]
	s_waitcnt vmcnt(7)
	ds_write_b128 v180, v[142:145] offset:27648
	global_load_dwordx4 v[142:145], v238, s[98:99]
	s_waitcnt lgkmcnt(8)
	v_mfma_f32_32x32x16_bf16 v[114:129], v[234:237], v[218:221], v[114:129]
	ds_read_b128 v[194:197], v179 offset:36928
	s_waitcnt lgkmcnt(7)
	v_mfma_f32_32x32x16_bf16 v[98:113], v[202:205], v[218:221], v[98:113]
	ds_read_b128 v[166:169], v178 offset:64
	s_waitcnt vmcnt(7)
	ds_write_b128 v180, v[146:149] offset:36864
	global_load_dwordx4 v[146:149], v206, s[100:101]
	s_waitcnt lgkmcnt(8)
	v_mfma_f32_32x32x16_bf16 v[82:97], v[234:237], v[222:225], v[82:97]
	ds_read_b128 v[198:201], v179 offset:41536
	v_mfma_f32_32x32x16_bf16 v[66:81], v[202:205], v[222:225], v[66:81]
	ds_read_b128 v[170:173], v178 offset:4672
	s_waitcnt vmcnt(7)
	ds_write_b128 v180, v[150:153] offset:46080
	global_load_dwordx4 v[150:153], v207, s[100:101]
	s_waitcnt lgkmcnt(9)
	v_mfma_f32_32x32x16_bf16 v[50:65], v[234:237], v[226:229], v[50:65]
	ds_read_b128 v[174:177], v178 offset:9280
	v_mfma_f32_32x32x16_bf16 v[34:49], v[202:205], v[226:229], v[34:49]
	ds_read_b128 v[190:193], v178 offset:13888
	s_waitcnt vmcnt(7)
	ds_write_b128 v180, v[154:157] offset:55296
	global_load_dwordx4 v[154:157], v208, s[100:101]
	s_waitcnt lgkmcnt(11)
	v_mfma_f32_32x32x16_bf16 v[18:33], v[234:237], v[230:233], v[18:33]
	v_mfma_f32_32x32x16_bf16 v[2:17], v[202:205], v[230:233], v[2:17]
	s_waitcnt vmcnt(7)
	ds_write_b128 v180, v[158:161] offset:64512
	global_load_dwordx4 v[158:161], v238, s[100:101]
	s_cmp_eq_u32 s32, 0
	s_cbranch_scc1 .Lg3_nd2_m2
	global_store_dwordx4 v253, v[210:213], s[50:51]
	v_add_u32_e32 v253, 0x21000, v253
; #define G5_LOAD(k0)                                                                 \
;   {                                                                                 \
;     _Pragma("unroll") for (int i_ = 0; i_ < 4; ++i_) ra[i_] = ldg16(Ap + (size_t)(i_ * 64) * lda + (k0)); \
;     _Pragma("unroll") for (int i_ = 0; i_ < 4; ++i_) rb[i_] = ldg16(Bp + (size_t)(i_ * 64) * ldb + (k0)); \
;   }
; #define G5_STORE(s)                                                                 \
;   {                                                                                 \
;     _Pragma("unroll") for (int i_ = 0; i_ < 4; ++i_) *(u32x4*)(Sw + (s) * STG + i_ * 64 * GS) = ra[i_]; \
;     _Pragma("unroll") for (int i_ = 0; i_ < 4; ++i_) *(u32x4*)(Sw + (s) * STG + 256 * GS + i_ * 64 * GS) = rb[i_]; \
;   }
; template <typename Epi>
; DI void gemm_tile512(const u16* __restrict__ A, int lda, const u16* __restrict__ Bt, int ldb, int K, char* lds_all, Epi epi) {
;     ...
;   const int nk = K >> 6;
;   __syncthreads();
;   G5_LOAD(0);
;   G5_STORE(0);
;   G5_LOAD(64);
;   __syncthreads();
;   for (int kt = 0; kt + 2 < nk; ++kt) {
;     const int cur = kt & 1;
;     G5_COMPUTE(cur);
;     G5_STORE(cur ^ 1);
;     G5_LOAD((kt + 2) << 6);
;     __syncthreads();
;   }
.Lg3_nd2_m2:
	v_subrev_u32_e32 v180, s11, v180
	s_waitcnt lgkmcnt(8)
	v_mfma_f32_32x32x16_bf16 v[114:129], v[194:197], v[166:169], v[114:129]
	ds_read_b128 v[234:237], v179 offset:36960
	s_waitcnt lgkmcnt(7)
	v_mfma_f32_32x32x16_bf16 v[98:113], v[198:201], v[166:169], v[98:113]
	ds_read_b128 v[218:221], v178 offset:96
	s_waitcnt lgkmcnt(7)
	v_mfma_f32_32x32x16_bf16 v[82:97], v[194:197], v[170:173], v[82:97]
	ds_read_b128 v[202:205], v179 offset:41568
	v_mfma_f32_32x32x16_bf16 v[66:81], v[198:201], v[170:173], v[66:81]
	ds_read_b128 v[222:225], v178 offset:4704
	s_waitcnt lgkmcnt(7)
	v_mfma_f32_32x32x16_bf16 v[50:65], v[194:197], v[174:177], v[50:65]
	ds_read_b128 v[226:229], v178 offset:9312
	v_mfma_f32_32x32x16_bf16 v[34:49], v[198:201], v[174:177], v[34:49]
	ds_read_b128 v[230:233], v178 offset:13920
	v_add_u32_e32 v178, s11, v178
	v_add_u32_e32 v179, s11, v179
	s_waitcnt lgkmcnt(8)
	v_mfma_f32_32x32x16_bf16 v[18:33], v[194:197], v[190:193], v[18:33]
	v_mfma_f32_32x32x16_bf16 v[2:17], v[198:201], v[190:193], v[2:17]
	s_sub_u32 s11, 0, s11
	s_add_u32 s98, s98, 0x80
	s_addc_u32 s99, s99, 0
	s_add_u32 s100, s100, 0x80
	s_addc_u32 s101, s101, 0
	s_waitcnt lgkmcnt(0)
	s_barrier
	ds_read_b128 v[194:197], v179 offset:36864
	ds_read_b128 v[166:169], v178
	v_mfma_f32_32x32x16_bf16 v[114:129], v[234:237], v[218:221], v[114:129]
	ds_read_b128 v[198:201], v179 offset:41472
	v_mfma_f32_32x32x16_bf16 v[98:113], v[202:205], v[218:221], v[98:113]
	ds_read_b128 v[170:173], v178 offset:4608
	v_mfma_f32_32x32x16_bf16 v[82:97], v[234:237], v[222:225], v[82:97]
	ds_read_b128 v[174:177], v178 offset:9216
	v_mfma_f32_32x32x16_bf16 v[66:81], v[202:205], v[222:225], v[66:81]
	ds_read_b128 v[190:193], v178 offset:13824
	v_mfma_f32_32x32x16_bf16 v[50:65], v[234:237], v[226:229], v[50:65]
	v_mfma_f32_32x32x16_bf16 v[34:49], v[202:205], v[226:229], v[34:49]
	v_mfma_f32_32x32x16_bf16 v[18:33], v[234:237], v[230:233], v[18:33]
	v_mfma_f32_32x32x16_bf16 v[2:17], v[202:205], v[230:233], v[2:17]
	s_waitcnt lgkmcnt(4)
	v_mfma_f32_32x32x16_bf16 v[114:129], v[194:197], v[166:169], v[114:129]
	ds_read_b128 v[234:237], v179 offset:36896
	s_waitcnt lgkmcnt(4)
	v_mfma_f32_32x32x16_bf16 v[98:113], v[198:201], v[166:169], v[98:113]
	ds_read_b128 v[218:221], v178 offset:32
	s_waitcnt vmcnt(7)
	ds_write_b128 v180, v[130:133]
	global_load_dwordx4 v[130:133], v206, s[98:99]
	s_waitcnt lgkmcnt(5)
	v_mfma_f32_32x32x16_bf16 v[82:97], v[194:197], v[170:173], v[82:97]
	ds_read_b128 v[202:205], v179 offset:41504
	v_mfma_f32_32x32x16_bf16 v[66:81], v[198:201], v[170:173], v[66:81]
	ds_read_b128 v[222:225], v178 offset:4640
	s_waitcnt vmcnt(7)
	ds_write_b128 v180, v[134:137] offset:9216
	global_load_dwordx4 v[134:137], v207, s[98:99]
	s_waitcnt lgkmcnt(7)
	v_mfma_f32_32x32x16_bf16 v[50:65], v[194:197], v[174:177], v[50:65]
	ds_read_b128 v[226:229], v178 offset:9248
	v_mfma_f32_32x32x16_bf16 v[34:49], v[198:201], v[174:177], v[34:49]
	ds_read_b128 v[230:233], v178 offset:13856
	s_waitcnt vmcnt(7)
	ds_write_b128 v180, v[138:141] offset:18432
	global_load_dwordx4 v[138:141], v208, s[98:99]
	s_waitcnt lgkmcnt(9)
	v_mfma_f32_32x32x16_bf16 v[18:33], v[194:197], v[190:193], v[18:33]
	v_mfma_f32_32x32x16_bf16 v[2:17], v[198:201], v[190:193], v[2:17]
	s_waitcnt vmcnt(7)
	ds_write_b128 v180, v[142:145] offset:27648
	global_load_dwordx4 v[142:145], v238, s[98:99]
	s_waitcnt lgkmcnt(8)
	v_mfma_f32_32x32x16_bf16 v[114:129], v[234:237], v[218:221], v[114:129]
	ds_read_b128 v[194:197], v179 offset:36928
	s_waitcnt lgkmcnt(7)
	v_mfma_f32_32x32x16_bf16 v[98:113], v[202:205], v[218:221], v[98:113]
	ds_read_b128 v[166:169], v178 offset:64
	s_waitcnt vmcnt(7)
	ds_write_b128 v180, v[146:149] offset:36864
	global_load_dwordx4 v[146:149], v206, s[100:101]
	s_waitcnt lgkmcnt(8)
	v_mfma_f32_32x32x16_bf16 v[82:97], v[234:237], v[222:225], v[82:97]
	ds_read_b128 v[198:201], v179 offset:41536
	v_mfma_f32_32x32x16_bf16 v[66:81], v[202:205], v[222:225], v[66:81]
	ds_read_b128 v[170:173], v178 offset:4672
	s_waitcnt vmcnt(7)
	ds_write_b128 v180, v[150:153] offset:46080
	global_load_dwordx4 v[150:153], v207, s[100:101]
	s_waitcnt lgkmcnt(9)
	v_mfma_f32_32x32x16_bf16 v[50:65], v[234:237], v[226:229], v[50:65]
	ds_read_b128 v[174:177], v178 offset:9280
	v_mfma_f32_32x32x16_bf16 v[34:49], v[202:205], v[226:229], v[34:49]
	ds_read_b128 v[190:193], v178 offset:13888
	s_waitcnt vmcnt(7)
	ds_write_b128 v180, v[154:157] offset:55296
	global_load_dwordx4 v[154:157], v208, s[100:101]
	s_waitcnt lgkmcnt(11)
	v_mfma_f32_32x32x16_bf16 v[18:33], v[234:237], v[230:233], v[18:33]
	v_mfma_f32_32x32x16_bf16 v[2:17], v[202:205], v[230:233], v[2:17]
	s_waitcnt vmcnt(7)
	ds_write_b128 v180, v[158:161] offset:64512
	global_load_dwordx4 v[158:161], v238, s[100:101]
	s_cmp_eq_u32 s32, 0
	s_cbranch_scc1 .Lg3_nd3_m2
	global_store_dwordx4 v253, v[240:243], s[50:51]
	v_add_u32_e32 v253, 0x21000, v253
; #define G5_LOAD(k0)                                                                 \
;   {                                                                                 \
;     _Pragma("unroll") for (int i_ = 0; i_ < 4; ++i_) ra[i_] = ldg16(Ap + (size_t)(i_ * 64) * lda + (k0)); \
;     _Pragma("unroll") for (int i_ = 0; i_ < 4; ++i_) rb[i_] = ldg16(Bp + (size_t)(i_ * 64) * ldb + (k0)); \
;   }
; #define G5_STORE(s)                                                                 \
;   {                                                                                 \
;     _Pragma("unroll") for (int i_ = 0; i_ < 4; ++i_) *(u32x4*)(Sw + (s) * STG + i_ * 64 * GS) = ra[i_]; \
;     _Pragma("unroll") for (int i_ = 0; i_ < 4; ++i_) *(u32x4*)(Sw + (s) * STG + 256 * GS + i_ * 64 * GS) = rb[i_]; \
;   }
; template <typename Epi>
; DI void gemm_tile512(const u16* __restrict__ A, int lda, const u16* __restrict__ Bt, int ldb, int K, char* lds_all, Epi epi) {
;     ...
;   const int nk = K >> 6;
;   __syncthreads();
;   G5_LOAD(0);
;   G5_STORE(0);
;   G5_LOAD(64);
;   __syncthreads();
;   for (int kt = 0; kt + 2 < nk; ++kt) {
;     const int cur = kt & 1;
;     G5_COMPUTE(cur);
;     G5_STORE(cur ^ 1);
;     G5_LOAD((kt + 2) << 6);
;     __syncthreads();
;   }
.Lg3_nd3_m2:
	v_subrev_u32_e32 v180, s11, v180
	s_waitcnt lgkmcnt(8)
	v_mfma_f32_32x32x16_bf16 v[114:129], v[194:197], v[166:169], v[114:129]
	ds_read_b128 v[234:237], v179 offset:36960
	s_waitcnt lgkmcnt(7)
	v_mfma_f32_32x32x16_bf16 v[98:113], v[198:201], v[166:169], v[98:113]
	ds_read_b128 v[218:221], v178 offset:96
	s_waitcnt lgkmcnt(7)
	v_mfma_f32_32x32x16_bf16 v[82:97], v[194:197], v[170:173], v[82:97]
	ds_read_b128 v[202:205], v179 offset:41568
	v_mfma_f32_32x32x16_bf16 v[66:81], v[198:201], v[170:173], v[66:81]
	ds_read_b128 v[222:225], v178 offset:4704
	s_waitcnt lgkmcnt(7)
	v_mfma_f32_32x32x16_bf16 v[50:65], v[194:197], v[174:177], v[50:65]
	ds_read_b128 v[226:229], v178 offset:9312
	v_mfma_f32_32x32x16_bf16 v[34:49], v[198:201], v[174:177], v[34:49]
	ds_read_b128 v[230:233], v178 offset:13920
	v_add_u32_e32 v178, s11, v178
	v_add_u32_e32 v179, s11, v179
	s_waitcnt lgkmcnt(8)
	v_mfma_f32_32x32x16_bf16 v[18:33], v[194:197], v[190:193], v[18:33]
	v_mfma_f32_32x32x16_bf16 v[2:17], v[198:201], v[190:193], v[2:17]
	s_sub_u32 s11, 0, s11
	s_add_u32 s98, s98, 0x80
	s_addc_u32 s99, s99, 0
	s_add_u32 s100, s100, 0x80
	s_addc_u32 s101, s101, 0
	s_waitcnt lgkmcnt(0)
	s_barrier
	ds_read_b128 v[194:197], v179 offset:36864
	ds_read_b128 v[166:169], v178
	v_mfma_f32_32x32x16_bf16 v[114:129], v[234:237], v[218:221], v[114:129]
	ds_read_b128 v[198:201], v179 offset:41472
	v_mfma_f32_32x32x16_bf16 v[98:113], v[202:205], v[218:221], v[98:113]
	ds_read_b128 v[170:173], v178 offset:4608
	v_mfma_f32_32x32x16_bf16 v[82:97], v[234:237], v[222:225], v[82:97]
	ds_read_b128 v[174:177], v178 offset:9216
	v_mfma_f32_32x32x16_bf16 v[66:81], v[202:205], v[222:225], v[66:81]
	ds_read_b128 v[190:193], v178 offset:13824
	v_mfma_f32_32x32x16_bf16 v[50:65], v[234:237], v[226:229], v[50:65]
	v_mfma_f32_32x32x16_bf16 v[34:49], v[202:205], v[226:229], v[34:49]
	v_mfma_f32_32x32x16_bf16 v[18:33], v[234:237], v[230:233], v[18:33]
	v_mfma_f32_32x32x16_bf16 v[2:17], v[202:205], v[230:233], v[2:17]
	s_waitcnt lgkmcnt(4)
	v_mfma_f32_32x32x16_bf16 v[114:129], v[194:197], v[166:169], v[114:129]
	ds_read_b128 v[234:237], v179 offset:36896
	s_waitcnt lgkmcnt(4)
	v_mfma_f32_32x32x16_bf16 v[98:113], v[198:201], v[166:169], v[98:113]
	ds_read_b128 v[218:221], v178 offset:32
	s_waitcnt vmcnt(7)
	ds_write_b128 v180, v[130:133]
	global_load_dwordx4 v[130:133], v206, s[98:99]
	s_waitcnt lgkmcnt(5)
	v_mfma_f32_32x32x16_bf16 v[82:97], v[194:197], v[170:173], v[82:97]
	ds_read_b128 v[202:205], v179 offset:41504
	v_mfma_f32_32x32x16_bf16 v[66:81], v[198:201], v[170:173], v[66:81]
	ds_read_b128 v[222:225], v178 offset:4640
	s_waitcnt vmcnt(7)
	ds_write_b128 v180, v[134:137] offset:9216
	global_load_dwordx4 v[134:137], v207, s[98:99]
	s_waitcnt lgkmcnt(7)
	v_mfma_f32_32x32x16_bf16 v[50:65], v[194:197], v[174:177], v[50:65]
	ds_read_b128 v[226:229], v178 offset:9248
	v_mfma_f32_32x32x16_bf16 v[34:49], v[198:201], v[174:177], v[34:49]
	ds_read_b128 v[230:233], v178 offset:13856
	s_waitcnt vmcnt(7)
	ds_write_b128 v180, v[138:141] offset:18432
	global_load_dwordx4 v[138:141], v208, s[98:99]
	s_waitcnt lgkmcnt(9)
	v_mfma_f32_32x32x16_bf16 v[18:33], v[194:197], v[190:193], v[18:33]
	v_mfma_f32_32x32x16_bf16 v[2:17], v[198:201], v[190:193], v[2:17]
	s_waitcnt vmcnt(7)
	ds_write_b128 v180, v[142:145] offset:27648
	global_load_dwordx4 v[142:145], v238, s[98:99]
	s_waitcnt lgkmcnt(8)
	v_mfma_f32_32x32x16_bf16 v[114:129], v[234:237], v[218:221], v[114:129]
	ds_read_b128 v[194:197], v179 offset:36928
	s_waitcnt lgkmcnt(7)
	v_mfma_f32_32x32x16_bf16 v[98:113], v[202:205], v[218:221], v[98:113]
	ds_read_b128 v[166:169], v178 offset:64
	s_waitcnt vmcnt(7)
	ds_write_b128 v180, v[146:149] offset:36864
	global_load_dwordx4 v[146:149], v206, s[100:101]
	s_waitcnt lgkmcnt(8)
	v_mfma_f32_32x32x16_bf16 v[82:97], v[234:237], v[222:225], v[82:97]
	ds_read_b128 v[198:201], v179 offset:41536
	v_mfma_f32_32x32x16_bf16 v[66:81], v[202:205], v[222:225], v[66:81]
	ds_read_b128 v[170:173], v178 offset:4672
	s_waitcnt vmcnt(7)
	ds_write_b128 v180, v[150:153] offset:46080
	global_load_dwordx4 v[150:153], v207, s[100:101]
	s_waitcnt lgkmcnt(9)
	v_mfma_f32_32x32x16_bf16 v[50:65], v[234:237], v[226:229], v[50:65]
	ds_read_b128 v[174:177], v178 offset:9280
	v_mfma_f32_32x32x16_bf16 v[34:49], v[202:205], v[226:229], v[34:49]
	ds_read_b128 v[190:193], v178 offset:13888
	s_waitcnt vmcnt(7)
	ds_write_b128 v180, v[154:157] offset:55296
	global_load_dwordx4 v[154:157], v208, s[100:101]
	s_waitcnt lgkmcnt(11)
	v_mfma_f32_32x32x16_bf16 v[18:33], v[234:237], v[230:233], v[18:33]
	v_mfma_f32_32x32x16_bf16 v[2:17], v[202:205], v[230:233], v[2:17]
	s_waitcnt vmcnt(7)
	ds_write_b128 v180, v[158:161] offset:64512
	global_load_dwordx4 v[158:161], v238, s[100:101]
	s_cmp_eq_u32 s32, 0
	s_cbranch_scc1 .Lg3_nd4_m2
	global_store_dwordx4 v253, v[244:247], s[50:51]
	v_add_u32_e32 v253, 0x21000, v253
.Lg3_nd4_m2:
	v_subrev_u32_e32 v180, s11, v180
	s_waitcnt lgkmcnt(8)
	v_mfma_f32_32x32x16_bf16 v[114:129], v[194:197], v[166:169], v[114:129]
	ds_read_b128 v[234:237], v179 offset:36960
	s_waitcnt lgkmcnt(7)
	v_mfma_f32_32x32x16_bf16 v[98:113], v[198:201], v[166:169], v[98:113]
	ds_read_b128 v[218:221], v178 offset:96
	s_waitcnt lgkmcnt(7)
	v_mfma_f32_32x32x16_bf16 v[82:97], v[194:197], v[170:173], v[82:97]
	ds_read_b128 v[202:205], v179 offset:41568
	v_mfma_f32_32x32x16_bf16 v[66:81], v[198:201], v[170:173], v[66:81]
	ds_read_b128 v[222:225], v178 offset:4704
	s_waitcnt lgkmcnt(7)
	v_mfma_f32_32x32x16_bf16 v[50:65], v[194:197], v[174:177], v[50:65]
	ds_read_b128 v[226:229], v178 offset:9312
	v_mfma_f32_32x32x16_bf16 v[34:49], v[198:201], v[174:177], v[34:49]
	ds_read_b128 v[230:233], v178 offset:13920
	v_add_u32_e32 v178, s11, v178
	v_add_u32_e32 v179, s11, v179
	s_waitcnt lgkmcnt(8)
	v_mfma_f32_32x32x16_bf16 v[18:33], v[194:197], v[190:193], v[18:33]
	v_mfma_f32_32x32x16_bf16 v[2:17], v[198:201], v[190:193], v[2:17]
	s_sub_u32 s11, 0, s11
	s_add_u32 s98, s98, 0x80
	s_addc_u32 s99, s99, 0
	s_add_u32 s100, s100, 0x80
	s_addc_u32 s101, s101, 0
	s_waitcnt lgkmcnt(0)
	s_mov_b32 s32, 0

; DI void gemm_phase(const Params& p, int layer, int mode, int nrows, char* lds_all) {
;     ...
;           } else {
;             const float a0 = fmaxf(v0.x, 0.f), a1 = fmaxf(v0.y, 0.f), a2 = fmaxf(v0.z, 0.f), a3 = fmaxf(v0.w, 0.f);
;             const float a4 = fmaxf(v1.x, 0.f), a5 = fmaxf(v1.y, 0.f), a6 = fmaxf(v1.z, 0.f), a7 = fmaxf(v1.w, 0.f);
;             uint4 o;
;             o.x = pack2(a0 * a0, a1 * a1); o.y = pack2(a2 * a2, a3 * a3); o.z = pack2(a4 * a4, a5 * a5); o.w = pack2(a6 * a6, a7 * a7);
;             *(uint4*)((u16*)(p.ws + O_Z) + (size_t)row * HP + col) = o;
;           }
.Lg3_nok2_m2:
	v_lshrrev_b32_e32 v237, 5, v165
	v_and_b32_e32 v194, 31, v165
	v_mul_u32_u24_e32 v235, 0x208, v237
	v_lshl_add_u32 v235, v194, 4, v235
	ds_read2_b64 v[2:5], v235 offset1:1
	v_add_u32_e32 v235, 0x2080, v235
	ds_read2_b64 v[6:9], v235 offset1:1
	v_add_u32_e32 v235, 0x2080, v235
	ds_read2_b64 v[10:13], v235 offset1:1
	v_add_u32_e32 v235, 0x2080, v235
	ds_read2_b64 v[14:17], v235 offset1:1
	v_add_u32_e32 v235, 0x2080, v235
	ds_read2_b64 v[18:21], v235 offset1:1
	v_add_u32_e32 v235, 0x2080, v235
	ds_read2_b64 v[22:25], v235 offset1:1
	v_add_u32_e32 v235, 0x2080, v235
	ds_read2_b64 v[26:29], v235 offset1:1
	v_add_u32_e32 v235, 0x2080, v235
	ds_read2_b64 v[30:33], v235 offset1:1
	v_add_u32_e32 v235, 0x2080, v235
	ds_read2_b64 v[34:37], v235 offset1:1
	v_add_u32_e32 v235, 0x2080, v235
	ds_read2_b64 v[38:41], v235 offset1:1
	v_add_u32_e32 v235, 0x2080, v235
	ds_read2_b64 v[42:45], v235 offset1:1
	v_add_u32_e32 v235, 0x2080, v235
	ds_read2_b64 v[182:185], v235 offset1:1
	v_add_u32_e32 v235, 0x2080, v235
	ds_read2_b64 v[186:189], v235 offset1:1
	v_add_u32_e32 v235, 0x2080, v235
	ds_read2_b64 v[210:213], v235 offset1:1
	v_add_u32_e32 v235, 0x2080, v235
	ds_read2_b64 v[240:243], v235 offset1:1
	v_add_u32_e32 v235, 0x2080, v235
	ds_read2_b64 v[244:247], v235 offset1:1
	s_waitcnt lgkmcnt(15)
	global_store_dwordx4 v234, v[2:5], s[50:51]
	v_add_u32_e32 v234, 0x21000, v234
	s_waitcnt lgkmcnt(14)
	global_store_dwordx4 v234, v[6:9], s[50:51]
	v_add_u32_e32 v234, 0x21000, v234
	s_waitcnt lgkmcnt(13)
	global_store_dwordx4 v234, v[10:13], s[50:51]
	v_add_u32_e32 v234, 0x21000, v234
	s_waitcnt lgkmcnt(12)
	global_store_dwordx4 v234, v[14:17], s[50:51]
	v_add_u32_e32 v234, 0x21000, v234
	s_waitcnt lgkmcnt(11)
	global_store_dwordx4 v234, v[18:21], s[50:51]
	v_add_u32_e32 v234, 0x21000, v234
	s_waitcnt lgkmcnt(10)
	global_store_dwordx4 v234, v[22:25], s[50:51]
	v_add_u32_e32 v234, 0x21000, v234
	s_waitcnt lgkmcnt(9)
	global_store_dwordx4 v234, v[26:29], s[50:51]
	v_add_u32_e32 v234, 0x21000, v234
	s_waitcnt lgkmcnt(8)
	global_store_dwordx4 v234, v[30:33], s[50:51]
	v_add_u32_e32 v234, 0x21000, v234
	s_waitcnt lgkmcnt(7)
	global_store_dwordx4 v234, v[34:37], s[50:51]
	v_add_u32_e32 v234, 0x21000, v234
	s_waitcnt lgkmcnt(6)
	global_store_dwordx4 v234, v[38:41], s[50:51]
	v_add_u32_e32 v234, 0x21000, v234
	s_waitcnt lgkmcnt(5)
	global_store_dwordx4 v234, v[42:45], s[50:51]
	v_add_u32_e32 v234, 0x21000, v234
	s_waitcnt lgkmcnt(0)
	v_mov_b32_e32 v253, v234
	s_mov_b32 s32, 1
	s_cmp_lg_u32 s10, 0
	s_cbranch_scc1 .Lg3_defer_m2
	global_store_dwordx4 v253, v[182:185], s[50:51]
	v_add_u32_e32 v253, 0x21000, v253
	global_store_dwordx4 v253, v[186:189], s[50:51]
	v_add_u32_e32 v253, 0x21000, v253
	global_store_dwordx4 v253, v[210:213], s[50:51]
	v_add_u32_e32 v253, 0x21000, v253
	global_store_dwordx4 v253, v[240:243], s[50:51]
	v_add_u32_e32 v253, 0x21000, v253
	global_store_dwordx4 v253, v[244:247], s[50:51]
	s_mov_b32 s32, 0
